# speedup vs baseline: 1.0099x; 1.0099x over previous
; #define BAR __builtin_amdgcn_s_barrier()
;     ...
;   for (int vw = blockIdx.x; vw < nwg; vw += gridDim.x) {
;     int tid_ = threadIdx.x;
;     asm volatile("" : "+v"(tid_));
;     const int wid = tid_ >> 6, lane = tid_ & 63, wr = wid >> 2, wc = wid & 3, fr = lane & 15, fq = lane >> 4;
;     int brow, bcol;
;     TILE_COORDS(vw, brow, bcol);
;     f32x4 acc[2][2][4][2] = {};
;     bf16x8 At[4][2], B0[2][2], B1[2][2];
;     STAGE(SB(0, 0), Bt, bcol, 0); STAGE(SA(0, 0), A, brow, 0);
;     STAGE(SB(0, 1), Bt, bcol + HALF, 0); STAGE(SA(0, 1), A, brow + HALF, 0);
;     if (wr == 1) BAR;
.LBB0_95:
	s_ashr_i32 s14, s30, 31
	s_lshr_b32 s14, s14, 29
	s_add_i32 s14, s30, s14
	s_ashr_i32 s15, s14, 3
	s_and_b32 s14, s14, -8
	s_sub_i32 s14, s30, s14
	s_cmp_lt_i32 s14, 0
	s_movk_i32 s16, 0x1b1
	s_cselect_b32 s16, s16, 0x1b0
	v_mov_b32_e32 v128, v194
	s_mul_i32 s14, s16, s14
	s_add_i32 s14, s14, s15
	v_ashrrev_i32_e32 v0, 31, v128
	s_mul_hi_i32 s15, s14, 0x4bda12f7
	v_lshrrev_b32_e32 v0, 26, v0
	s_lshr_b32 s16, s15, 31
	s_ashr_i32 s15, s15, 5
	v_add_u32_e32 v0, v128, v0
	s_add_i32 s20, s15, s16
	v_ashrrev_i32_e32 v1, 6, v0
	v_bfe_i32 v0, v128, 27, 1
	s_mul_i32 s15, s20, 0x6c
	v_lshlrev_b32_e32 v143, 4, v128
	v_lshrrev_b32_e32 v0, 22, v0
	s_sub_i32 s14, s14, s15
	v_add_u32_e32 v0, v143, v0
	s_bfe_i32 s15, s14, 0x80000
	v_and_b32_e32 v0, 0xfffffc00, v0
	s_bfe_u32 s15, s15, 0x2000d
	v_sub_u32_e32 v0, v143, v0
	s_add_i32 s15, s14, s15
	v_lshrrev_b32_e32 v2, 4, v0
	s_bfe_i32 s16, s15, 0x80000
	s_and_b32 s15, s15, 0xfc
	v_bitop3_b32 v2, v2, v0, 32 bitop3:0x6c
	s_sub_i32 s14, s14, s15
	v_ashrrev_i32_e32 v3, 31, v2
	s_sext_i32_i16 s16, s16
	s_sext_i32_i8 s14, s14
	v_lshrrev_b32_e32 v3, 26, v3
	s_lshl_b32 s21, s14, 8
	s_lshl_b32 s14, s16, 6
	v_add_u32_e32 v3, v2, v3
	s_and_b32 s14, s14, 0xffffff00
	v_lshlrev_b32_e32 v0, 3, v1
	v_ashrrev_i32_e32 v4, 6, v3
	v_and_b32_e32 v3, 0xc0, v3
	s_ashr_i32 s15, s14, 31
	v_and_b32_e32 v0, -16, v0
	v_lshlrev_b32_e32 v1, 5, v1
	v_sub_u32_e32 v2, v2, v3
	s_lshl_b64 s[18:19], s[14:15], 12
	v_add_u32_e32 v0, v4, v0
	v_and_b32_e32 v1, 32, v1
	v_ashrrev_i16_sdwa v2, v142, sext(v2) dst_sel:DWORD dst_unused:UNUSED_PAD src0_sel:DWORD src1_sel:BYTE_0
	s_add_u32 s16, s82, s18
	v_add_u32_sdwa v2, v1, sext(v2) dst_sel:DWORD dst_unused:UNUSED_PAD src0_sel:DWORD src1_sel:WORD_0
	v_ashrrev_i32_e32 v1, 31, v0
	s_addc_u32 s17, s83, s19
	v_lshlrev_b64 v[0:1], 12, v[0:1]
	v_ashrrev_i32_e32 v3, 31, v2
	v_lshl_add_u64 v[4:5], s[16:17], 0, v[0:1]
	v_lshlrev_b64 v[2:3], 1, v[2:3]
	v_add_u32_e32 v20, 0x2000, v143
	v_lshl_add_u64 v[8:9], v[4:5], 0, v[2:3]
	v_ashrrev_i32_e32 v4, 31, v20
	v_lshrrev_b32_e32 v4, 22, v4
	v_add_u32_e32 v4, v20, v4
	v_ashrrev_i32_e32 v5, 10, v4
	v_mul_i32_i24_e32 v4, 0x400, v5
	v_sub_u32_e32 v4, v20, v4
	v_lshrrev_b32_e32 v6, 4, v4
	v_bitop3_b32 v6, v6, v4, 32 bitop3:0x6c
	v_ashrrev_i32_e32 v7, 31, v6
	v_lshrrev_b32_e32 v7, 26, v7
	v_add_u32_e32 v7, v6, v7
	v_lshlrev_b32_e32 v4, 3, v5
	v_ashrrev_i32_e32 v10, 6, v7
	v_and_b32_e32 v7, 0xc0, v7
	v_and_b32_e32 v4, -16, v4
	v_lshlrev_b32_e32 v5, 5, v5
	v_sub_u32_e32 v6, v6, v7
	v_add_u32_e32 v4, v10, v4
	v_and_b32_e32 v5, 32, v5
	v_ashrrev_i16_sdwa v6, v142, sext(v6) dst_sel:DWORD dst_unused:UNUSED_PAD src0_sel:DWORD src1_sel:BYTE_0
	v_add_u32_e32 v147, s24, v143
	v_add_u32_sdwa v6, v5, sext(v6) dst_sel:DWORD dst_unused:UNUSED_PAD src0_sel:DWORD src1_sel:WORD_0
	v_ashrrev_i32_e32 v5, 31, v4
	v_readfirstlane_b32 s22, v147
	v_lshlrev_b64 v[4:5], 12, v[4:5]
	v_add_u32_e32 v12, s24, v20
	s_mov_b32 m0, s22
	v_lshl_add_u64 v[10:11], s[16:17], 0, v[4:5]
	v_readfirstlane_b32 s16, v12
	global_load_lds_dwordx4 v[8:9], off
	s_mov_b32 m0, s16
	s_lshl_b32 s16, s20, 10
	s_add_i32 s16, s21, s16
	s_ashr_i32 s17, s16, 31
	s_lshl_b64 s[20:21], s[16:17], 12
	s_add_u32 s22, s78, s20
	s_addc_u32 s23, s79, s21
	v_lshl_add_u64 v[12:13], s[22:23], 0, v[0:1]
	v_lshl_add_u64 v[14:15], s[22:23], 0, v[4:5]
	s_or_b32 s22, s14, 0x80
	s_ashr_i32 s23, s22, 31
	s_lshl_b64 s[22:23], s[22:23], 12
	s_add_u32 s22, s82, s22
	v_ashrrev_i32_e32 v7, 31, v6
	s_addc_u32 s23, s83, s23
	v_lshlrev_b64 v[6:7], 1, v[6:7]
	v_add_u32_e32 v153, 0, v143
	v_lshl_add_u64 v[16:17], s[22:23], 0, v[0:1]
	v_lshl_add_u64 v[18:19], s[22:23], 0, v[4:5]
	s_or_b32 s22, s16, 0x80
	v_lshl_add_u64 v[10:11], v[10:11], 0, v[6:7]
	v_readfirstlane_b32 s17, v153
	v_add_u32_e32 v154, 0x2000, v153
	s_ashr_i32 s23, s22, 31
	global_load_lds_dwordx4 v[10:11], off
	v_lshl_add_u64 v[12:13], v[12:13], 0, v[2:3]
	s_mov_b32 m0, s17
	v_readfirstlane_b32 s17, v154
	v_add_u32_e32 v155, s25, v143
	s_lshl_b64 s[22:23], s[22:23], 12
	global_load_lds_dwordx4 v[12:13], off
	v_lshl_add_u64 v[14:15], v[14:15], 0, v[6:7]
	s_mov_b32 m0, s17
	v_readfirstlane_b32 s17, v155
	v_add_u32_e32 v20, s25, v20
	s_add_u32 s22, s78, s22
	global_load_lds_dwordx4 v[14:15], off
	v_lshl_add_u64 v[16:17], v[16:17], 0, v[2:3]
	s_mov_b32 m0, s17
	v_readfirstlane_b32 s17, v20
	s_addc_u32 s23, s79, s23
	v_add_u32_e32 v157, 0x4000, v153
	global_load_lds_dwordx4 v[16:17], off
	v_lshl_add_u64 v[18:19], v[18:19], 0, v[6:7]
	s_mov_b32 m0, s17
	v_lshl_add_u64 v[20:21], s[22:23], 0, v[0:1]
	v_readfirstlane_b32 s17, v157
	v_add_u32_e32 v158, 0x6000, v153
	global_load_lds_dwordx4 v[18:19], off
	v_lshl_add_u64 v[130:131], v[20:21], 0, v[2:3]
	s_mov_b32 m0, s17
	v_lshl_add_u64 v[20:21], s[22:23], 0, v[4:5]
	v_readfirstlane_b32 s17, v158
	global_load_lds_dwordx4 v[130:131], off
	v_lshl_add_u64 v[132:133], v[20:21], 0, v[6:7]
	s_mov_b32 m0, s17
	v_ashrrev_i32_e32 v20, 8, v128
	global_load_lds_dwordx4 v[132:133], off
	v_mov_b64_e32 v[22:23], 0
	v_mov_b64_e32 v[24:25], 0
	v_mov_b64_e32 v[26:27], 0
	v_mov_b64_e32 v[28:29], 0
	v_mov_b64_e32 v[30:31], 0
	v_mov_b64_e32 v[32:33], 0
	v_mov_b64_e32 v[34:35], 0
	v_mov_b64_e32 v[36:37], 0
	v_mov_b64_e32 v[38:39], 0
	v_mov_b64_e32 v[40:41], 0
	v_mov_b64_e32 v[42:43], 0
	v_mov_b64_e32 v[44:45], 0
	v_mov_b64_e32 v[46:47], 0
	v_mov_b64_e32 v[48:49], 0
	v_mov_b64_e32 v[50:51], 0
	v_mov_b64_e32 v[52:53], 0
	v_mov_b64_e32 v[54:55], 0
	v_mov_b64_e32 v[56:57], 0
	v_mov_b64_e32 v[58:59], 0
	v_mov_b64_e32 v[60:61], 0
	v_mov_b64_e32 v[62:63], 0
	v_mov_b64_e32 v[64:65], 0
	v_mov_b64_e32 v[66:67], 0
	v_mov_b64_e32 v[68:69], 0
	v_mov_b64_e32 v[70:71], 0
	v_mov_b64_e32 v[72:73], 0
	v_mov_b64_e32 v[74:75], 0
	v_mov_b64_e32 v[76:77], 0
	v_mov_b64_e32 v[78:79], 0
	v_mov_b64_e32 v[80:81], 0
	v_mov_b64_e32 v[82:83], 0
	v_mov_b64_e32 v[84:85], 0
	v_mov_b64_e32 v[86:87], 0
	v_mov_b64_e32 v[88:89], 0
	v_mov_b64_e32 v[90:91], 0
	v_mov_b64_e32 v[92:93], 0
	v_mov_b64_e32 v[94:95], 0
	v_mov_b64_e32 v[96:97], 0
	v_mov_b64_e32 v[98:99], 0
	v_mov_b64_e32 v[100:101], 0
	v_mov_b64_e32 v[102:103], 0
	v_mov_b64_e32 v[104:105], 0
	v_mov_b64_e32 v[106:107], 0
	v_mov_b64_e32 v[108:109], 0
	v_mov_b64_e32 v[110:111], 0
	v_mov_b64_e32 v[112:113], 0
	v_mov_b64_e32 v[114:115], 0
	v_mov_b64_e32 v[116:117], 0
	v_mov_b64_e32 v[118:119], 0
	v_mov_b64_e32 v[120:121], 0
	v_mov_b64_e32 v[122:123], 0
	v_mov_b64_e32 v[124:125], 0
	v_mov_b64_e32 v[126:127], 0
	v_cmp_eq_u32_e32 vcc, 1, v20
	s_and_saveexec_b64 s[22:23], vcc
	s_cbranch_execz .LBB0_97
	s_barrier
; #define WAIT_V(n) asm volatile("s_waitcnt vmcnt(" #n ")" ::: "memory")
; #define BAR __builtin_amdgcn_s_barrier()
;     ...
;     WAIT_V(4); BAR;
;     STAGE(SB(1, 0), Bt, bcol, 1); STAGE(SA(1, 0), A, brow, 1); STAGE(SB(1, 1), Bt, bcol + HALF, 1);
;     WAIT_V(6); BAR;
.LBB0_97:
	s_or_b64 exec, exec, s[22:23]
	v_add_u32_e32 v159, s26, v143
	v_add_u32_e32 v160, 0x2000, v159
	v_readfirstlane_b32 s17, v159
	v_lshl_add_u64 v[8:9], v[8:9], 0, s[0:1]
	s_mov_b32 m0, s17
	v_readfirstlane_b32 s17, v160
	v_add_u32_e32 v161, 0x8000, v153
	s_waitcnt vmcnt(2)
	s_barrier
	global_load_lds_dwordx4 v[8:9], off
	v_lshl_add_u64 v[8:9], v[10:11], 0, s[0:1]
	s_mov_b32 m0, s17
	v_readfirstlane_b32 s17, v161
	v_add_u32_e32 v162, 0xa000, v153
	global_load_lds_dwordx4 v[8:9], off
	v_lshl_add_u64 v[8:9], v[12:13], 0, s[0:1]
	s_mov_b32 m0, s17
	v_readfirstlane_b32 s17, v162
	v_add_u32_e32 v163, s27, v143
	global_load_lds_dwordx4 v[8:9], off
	v_lshl_add_u64 v[8:9], v[14:15], 0, s[0:1]
	s_mov_b32 m0, s17
	v_readfirstlane_b32 s17, v163
	v_add_u32_e32 v164, 0x2000, v163
	global_load_lds_dwordx4 v[8:9], off
	v_lshl_add_u64 v[8:9], v[16:17], 0, s[0:1]
	s_mov_b32 m0, s17
	v_readfirstlane_b32 s17, v164
	global_load_lds_dwordx4 v[8:9], off
	v_lshl_add_u64 v[8:9], v[18:19], 0, s[0:1]
	s_mov_b32 m0, s17
	v_and_b32_e32 v21, 15, v128
	global_load_lds_dwordx4 v[8:9], off
	v_bfe_u32 v145, v128, 4, 2
	v_lshlrev_b32_e32 v11, 2, v128
	v_lshlrev_b32_e32 v8, 4, v145
	v_lshlrev_b32_e32 v9, 6, v21
	v_and_b32_e32 v11, 32, v11
	v_bitop3_b32 v9, v8, v11, v9 bitop3:0x36
	v_add_u32_e32 v12, s24, v9
	v_add_u32_e32 v13, s25, v9
	v_add_u32_e32 v14, s26, v9
	v_add_u32_e32 v15, s27, v9
	v_add_u32_e32 v17, 0, v9
	v_lshlrev_b32_e32 v9, 6, v128
	s_movk_i32 s17, 0x3c0
	v_and_or_b32 v8, v9, s17, v8
	v_xad_u32 v11, v8, v11, 0
	v_lshl_add_u64 v[8:9], s[18:19], 0, v[0:1]
	v_lshl_add_u64 v[0:1], s[20:21], 0, v[0:1]
	v_lshl_add_u64 v[0:1], v[0:1], 0, v[2:3]
	v_lshl_add_u64 v[8:9], v[8:9], 0, v[2:3]
	v_lshl_add_u64 v[138:139], s[78:79], 0, v[0:1]
	v_lshl_add_u64 v[0:1], s[20:21], 0, v[4:5]
	v_bfe_u32 v144, v128, 6, 2
	s_waitcnt vmcnt(6)
	v_lshlrev_b32_e32 v16, 13, v20
	v_lshl_add_u64 v[134:135], s[82:83], 0, v[8:9]
	v_lshl_add_u64 v[8:9], s[18:19], 0, v[4:5]
	v_lshl_add_u64 v[0:1], v[0:1], 0, v[6:7]
	v_lshlrev_b32_e32 v10, 12, v144
	v_lshl_or_b32 v146, v20, 6, v21
	v_or_b32_e32 v18, 0x800, v16
	v_or_b32_e32 v19, 0x1000, v16
	v_or_b32_e32 v20, 0x1800, v16
	v_lshl_add_u64 v[8:9], v[8:9], 0, v[6:7]
	v_lshl_add_u64 v[140:141], s[78:79], 0, v[0:1]
	v_mov_b32_e32 v0, 0
	v_lshl_add_u64 v[136:137], s[82:83], 0, v[8:9]
	s_mov_b32 s17, -2
	s_mov_b64 s[18:19], 0
	v_add_u32_e32 v166, v12, v10
	v_add_u32_e32 v151, v17, v16
	v_add_u32_e32 v150, v11, v18
	v_add_u32_e32 v149, v11, v19
	v_add_u32_e32 v148, v11, v20
	v_add_u32_e32 v165, v13, v10
	v_add_u32_e32 v156, v14, v10
	v_add_u32_e32 v152, v15, v10
	v_mov_b32_e32 v1, v0
	v_mov_b32_e32 v2, v0
	v_mov_b32_e32 v3, v0
	v_mov_b32_e32 v4, v0
	v_mov_b32_e32 v5, v0
	v_mov_b32_e32 v6, v0
	v_mov_b32_e32 v7, v0
	v_mov_b32_e32 v8, v0
	v_mov_b32_e32 v9, v0
	v_mov_b32_e32 v10, v0
	v_mov_b32_e32 v11, v0
	v_mov_b32_e32 v12, v0
	v_mov_b32_e32 v13, v0
	v_mov_b32_e32 v14, v0
	v_mov_b32_e32 v15, v0
	v_mov_b32_e32 v16, v0
	v_mov_b32_e32 v17, v0
	v_mov_b32_e32 v18, v0
	v_mov_b32_e32 v19, v0
	v_mov_b32_e32 v20, v0
	v_mov_b32_e32 v21, v0
	s_barrier

; __device__ __forceinline__ void nsa_prep_tile(const Params& p, int pt, char* smem) {
;   const int tid = opaque_tid(), lane = tid & 63, wid = tid >> 6;
;   const long tok0 = (long)pt * 64;
;   u16* vt = (u16*)smem;
;   u16* Z = p.Z;
;   const int hi = lane >> 5, l5 = lane & 31;
;   const int kcol = hi ? 6144 : 5632, vcol = hi ? 6400 : 5888;
;   const float* qgp = p.q_gain + (lane & 7) * 16;
;   const float* kgp = p.k_gain + (hi ? 256 : 128) + (l5 & 15) * 8;
; #pragma unroll 1
;   for (int r0 = 0; r0 < 8; r0 += 4) {
;     uint4 q0[4], q1[4], kr[4];
;     uint4 vr0, vr1, vr2, vr3;
; #pragma unroll
;     for (int r = 0; r < 4; ++r) {
;       const u16* zr = Z + (tok0 + wid * 8 + r0 + r) * LDZ0;
;       q0[r] = *(const uint4*)(zr + 3072 + lane * 16);
;       q1[r] = *(const uint4*)(zr + 3072 + lane * 16 + 8);
;       kr[r] = *(const uint4*)(zr + kcol + l5 * 8);
;     }
.LBB0_180:
	s_cmpk_gt_i32 s2, 0xff
	s_mov_b64 s[0:1], -1
	s_cbranch_scc0 .LBB0_212
	s_cmpk_lt_u32 s2, 0x200
	s_cbranch_scc1 .LBB0_185
	v_mov_b32_e32 v1, v194
	s_waitcnt vmcnt(11)
	v_mov_b32_e32 v7, v0
	v_and_b32_e32 v3, 63, v1
	v_lshlrev_b32_e32 v77, 6, v1
	v_cmp_gt_u32_e32 vcc, 32, v3
	v_and_b32_e32 v6, 0x1c0, v77
	v_lshl_add_u64 v[66:67], s[66:67], 0, v[6:7]
	v_cndmask_b32_e32 v6, v146, v147, vcc
	s_waitcnt vmcnt(10)
	v_lshlrev_b32_e32 v8, 5, v1
	v_lshl_add_u64 v[6:7], s[36:37], 0, v[6:7]
	v_and_b32_e32 v8, 0x1e0, v8
	v_mov_b32_e32 v9, v0
	v_lshl_add_u64 v[68:69], v[6:7], 0, v[8:9]
	v_ashrrev_i32_e32 v6, 3, v1
	s_add_i32 s8, s2, 0xfffffe00
	v_cndmask_b32_e32 v2, v142, v143, vcc
	v_cndmask_b32_e32 v4, v144, v145, vcc
	v_and_b32_e32 v70, -8, v6
	v_cmp_lt_i32_e32 vcc, v149, v150
	s_lshl_b32 s4, s8, 6
	s_mov_b32 s5, s35
	v_ashrrev_i32_e32 v71, 31, v70
	v_lshlrev_b32_e32 v6, 4, v3
	v_cndmask_b32_e32 v3, v148, v149, vcc
	v_cmp_lt_i32_e32 vcc, v151, v150
	v_lshlrev_b32_e32 v10, 3, v1
	v_lshl_add_u64 v[72:73], v[70:71], 0, s[4:5]
	v_readlane_b32 s16, v248, 45
	v_lshlrev_b32_e32 v71, 2, v3
	v_cndmask_b32_e32 v3, v148, v151, vcc
	v_cmp_lt_i32_e32 vcc, v152, v150
	v_mov_b32_e32 v5, v0
	v_and_b32_e32 v8, 0xf8, v10
	v_readlane_b32 s24, v248, 53
	v_readlane_b32 s25, v248, 54
	v_lshlrev_b32_e32 v90, 2, v3
	v_cndmask_b32_e32 v3, v148, v152, vcc
	v_cmp_lt_i32_e32 vcc, v153, v150
	v_lshl_add_u64 v[4:5], s[24:25], 0, v[4:5]
	v_lshlrev_b32_e32 v10, 1, v8
	v_mov_b32_e32 v11, v0
	v_lshlrev_b32_e32 v91, 2, v3
	v_cndmask_b32_e32 v3, v148, v153, vcc
	s_mov_b32 s0, 0
	v_lshl_add_u64 v[74:75], v[4:5], 0, v[10:11]
	v_lshlrev_b32_e32 v92, 2, v3
	v_add_u32_e32 v76, 0, v6
	s_mov_b64 s[6:7], -1
	v_lshlrev_b32_e32 v78, 1, v6
	v_mov_b32_e32 v79, v0
	v_lshlrev_b32_e32 v80, 1, v2
	v_mov_b32_e32 v81, v0
	v_lshlrev_b32_e32 v82, 1, v8
	v_mov_b32_e32 v83, v0
	v_readlane_b32 s17, v248, 46
	v_readlane_b32 s18, v248, 47
	v_readlane_b32 s19, v248, 48
	v_readlane_b32 s20, v248, 49
	v_readlane_b32 s21, v248, 50
	v_readlane_b32 s22, v248, 51
	v_readlane_b32 s23, v248, 52
	v_readlane_b32 s26, v248, 55
	v_readlane_b32 s27, v248, 56
	v_readlane_b32 s28, v248, 57
	v_readlane_b32 s29, v248, 58
	v_readlane_b32 s30, v248, 59
	v_readlane_b32 s31, v248, 60
	global_load_dwordx4 v[210:213], v[66:67], off offset:48
	global_load_dwordx4 v[214:217], v[66:67], off offset:32
	global_load_dwordx4 v[218:221], v[66:67], off offset:16
	global_load_dwordx4 v[222:225], v[66:67], off
	global_load_dwordx4 v[226:229], v[68:69], off offset:16
	global_load_dwordx4 v[230:233], v[68:69], off
	s_waitcnt vmcnt(0)
.LBB0_183:
	s_waitcnt vmcnt(8)
	v_or_b32_e32 v18, s0, v72
	v_mad_u64_u32 v[2:3], s[16:17], v18, s77, v[84:85]
	v_mad_i32_i24 v3, v73, s77, v3
	v_lshl_add_u64 v[4:5], v[2:3], 0, v[78:79]
	v_add_co_u32_e32 v8, vcc, 0x1000, v4
	v_lshl_add_u64 v[6:7], v[4:5], 0, s[46:47]
	s_nop 0
	v_addc_co_u32_e32 v9, vcc, 0, v5, vcc
	global_load_dwordx4 v[62:65], v[8:9], off offset:2048
	global_load_dwordx4 v[58:61], v[6:7], off offset:16
	v_lshl_add_u64 v[2:3], v[2:3], 0, v[80:81]
	v_lshl_add_u64 v[2:3], v[2:3], 0, v[82:83]
	global_load_dwordx4 v[54:57], v[2:3], off
	s_movk_i32 s1, 0x4000
	s_mov_b64 s[16:17], 0x4e00
	v_add_co_u32_e32 v8, vcc, s1, v4
	v_lshl_add_u64 v[6:7], v[4:5], 0, s[16:17]
	s_nop 0
	v_addc_co_u32_e32 v9, vcc, 0, v5, vcc
	global_load_dwordx4 v[46:49], v[8:9], off offset:3584
	global_load_dwordx4 v[42:45], v[6:7], off offset:16
	v_add_co_u32_e32 v6, vcc, s39, v2
	s_mov_b32 s1, 0x8000
	s_nop 0
	v_addc_co_u32_e32 v7, vcc, 0, v3, vcc
	s_mov_b64 s[16:17], 0x8400
	v_add_co_u32_e32 v8, vcc, s1, v4
	global_load_dwordx4 v[38:41], v[6:7], off offset:1536
	v_lshl_add_u64 v[6:7], v[4:5], 0, s[16:17]
	v_addc_co_u32_e32 v9, vcc, 0, v5, vcc
	global_load_dwordx4 v[30:33], v[8:9], off offset:1024
	global_load_dwordx4 v[26:29], v[6:7], off offset:16
	v_add_co_u32_e32 v6, vcc, s40, v2
	s_mov_b64 s[16:17], 0xba00
	s_nop 0
	v_addc_co_u32_e32 v7, vcc, 0, v3, vcc
	s_mov_b32 s1, 0xb000
	global_load_dwordx4 v[22:25], v[6:7], off offset:3072
	v_lshl_add_u64 v[6:7], v[4:5], 0, s[16:17]
	v_add_co_u32_e32 v4, vcc, s1, v4
	v_or_b32_e32 v88, s0, v70
	s_nop 0
	v_addc_co_u32_e32 v5, vcc, 0, v5, vcc
	v_add_co_u32_e32 v2, vcc, s41, v2
	global_load_dwordx4 v[14:17], v[4:5], off offset:2560
	global_load_dwordx4 v[10:13], v[6:7], off offset:16
	v_addc_co_u32_e32 v3, vcc, 0, v3, vcc
	global_load_dwordx4 v[6:9], v[2:3], off offset:512
	v_mad_u64_u32 v[2:3], s[16:17], v18, s77, v[74:75]
	v_mad_i32_i24 v3, v73, s77, v3
	v_add_co_u32_e32 v4, vcc, s39, v2
	global_load_dwordx4 v[50:53], v[2:3], off
	s_nop 0
	v_addc_co_u32_e32 v5, vcc, 0, v3, vcc
	global_load_dwordx4 v[34:37], v[4:5], off offset:1536
	v_add_co_u32_e32 v4, vcc, s40, v2
	v_ashrrev_i32_e32 v89, 31, v88
	s_nop 0
	v_addc_co_u32_e32 v5, vcc, 0, v3, vcc
	v_add_co_u32_e32 v2, vcc, s41, v2
	v_lshl_add_u64 v[94:95], v[88:89], 0, s[4:5]
	s_nop 0
	v_addc_co_u32_e32 v3, vcc, 0, v3, vcc
	v_mad_u64_u32 v[102:103], s[0:1], v94, s77, v[84:85]
	global_load_dwordx4 v[18:21], v[4:5], off offset:3072
	v_mad_i32_i24 v103, v95, s77, v103
	global_load_dwordx4 v[2:5], v[2:3], off offset:512
	s_waitcnt vmcnt(15)
	v_lshlrev_b32_e32 v104, 16, v62
	v_and_b32_e32 v105, 0xffff0000, v62
	v_lshlrev_b32_e32 v108, 16, v63
	v_and_b32_e32 v109, 0xffff0000, v63
	v_lshlrev_b32_e32 v110, 16, v64
	v_and_b32_e32 v111, 0xffff0000, v64
	v_lshlrev_b32_e32 v112, 16, v65
	v_and_b32_e32 v113, 0xffff0000, v65
	s_waitcnt vmcnt(14)
; __device__ __forceinline__ void nsa_prep_tile(const Params& p, int pt, char* smem) {
;     ...
;     for (int r = 0; r < 4; ++r) {
;       const int tl = wid * 8 + r0 + r;
;       u16* zr = Z + (tok0 + tl) * LDZ0;
;       {
;         u16* qp = zr + 3072 + lane * 16;
;         float f[16];
;         unpack8(q0[r], f);
;         unpack8(q1[r], f + 8);
;         float ss = 0.f;
; #pragma unroll
;         for (int i = 0; i < 16; ++i) ss += f[i] * f[i];
;         ss += __shfl_xor(ss, 1); ss += __shfl_xor(ss, 2); ss += __shfl_xor(ss, 4);
;         float rr = rsqrtf(ss * (1.f / 128.f) + EPS) * (0.08838834764831845f * 1.4426950408889634f);
; #pragma unroll
;         for (int i = 0; i < 16; ++i) f[i] = f[i] * rr * qgp[i];
;         *(uint4*)qp = pack8(f);
;         *(uint4*)(qp + 8) = pack8(f + 8);
;       }
	v_lshlrev_b32_e32 v114, 16, v58
	v_and_b32_e32 v115, 0xffff0000, v58
	v_lshlrev_b32_e32 v116, 16, v59
	v_and_b32_e32 v117, 0xffff0000, v59
	v_lshlrev_b32_e32 v118, 16, v60
	v_and_b32_e32 v119, 0xffff0000, v60
	v_lshlrev_b32_e32 v120, 16, v61
	v_and_b32_e32 v121, 0xffff0000, v61
	s_nop 1
	v_mov_b64_e32 v[58:59], v[210:211]
	v_mov_b64_e32 v[60:61], v[212:213]
	s_nop 1
	v_mov_b64_e32 v[62:63], v[214:215]
	v_mov_b64_e32 v[64:65], v[216:217]
	s_nop 1
	v_mov_b64_e32 v[94:95], v[218:219]
	v_mov_b64_e32 v[96:97], v[220:221]
	s_nop 1
	v_mov_b64_e32 v[98:99], v[222:223]
	v_mov_b64_e32 v[100:101], v[224:225]
	v_pk_mul_f32 v[134:135], v[104:105], v[104:105]
	v_pk_mul_f32 v[132:133], v[108:109], v[108:109]
	v_add_f32_e32 v89, v134, v135
	v_add_f32_e32 v89, v89, v132
	v_pk_mul_f32 v[130:131], v[110:111], v[110:111]
	v_add_f32_e32 v89, v133, v89
	v_add_f32_e32 v89, v130, v89
	v_add_f32_e32 v106, v131, v89
	v_fmac_f32_e32 v106, v112, v112
	s_waitcnt vmcnt(13)
	v_lshlrev_b32_e32 v136, 16, v54
	v_and_b32_e32 v137, 0xffff0000, v54
	v_pk_mul_f32 v[128:129], v[114:115], v[114:115]
	v_pk_fma_f32 v[130:131], v[112:113], v[112:113], v[106:107] op_sel_hi:[1,1,0]
	v_lshlrev_b32_e32 v138, 16, v55
	v_and_b32_e32 v139, 0xffff0000, v55
	v_pk_mul_f32 v[158:159], v[136:137], v[136:137]
	v_pk_mul_f32 v[156:157], v[138:139], v[138:139]
	v_mov_b32_e32 v160, v158
	v_mov_b32_e32 v161, v128
	v_mov_b32_e32 v130, v159
	v_pk_mul_f32 v[126:127], v[116:117], v[116:117]
	v_lshlrev_b32_e32 v140, 16, v56
	v_and_b32_e32 v141, 0xffff0000, v56
	v_pk_add_f32 v[130:131], v[160:161], v[130:131]
	v_mov_b32_e32 v128, v156
	v_lshlrev_b32_e32 v154, 16, v57
	v_and_b32_e32 v155, 0xffff0000, v57
	v_pk_mul_f32 v[56:57], v[140:141], v[140:141]
	v_pk_add_f32 v[128:129], v[130:131], v[128:129]
	v_pk_mov_b32 v[130:131], v[156:157], v[126:127] op_sel:[1,0]
	v_pk_mul_f32 v[124:125], v[118:119], v[118:119]
	v_pk_add_f32 v[128:129], v[130:131], v[128:129]
	v_mov_b32_e32 v126, v56
	v_pk_mul_f32 v[54:55], v[154:155], v[154:155]
	v_pk_add_f32 v[126:127], v[126:127], v[128:129]
	v_pk_mov_b32 v[56:57], v[56:57], v[124:125] op_sel:[1,0]
	v_pk_mul_f32 v[122:123], v[120:121], v[120:121]
	v_pk_add_f32 v[56:57], v[56:57], v[126:127]
	v_mov_b32_e32 v124, v54
	v_pk_add_f32 v[56:57], v[124:125], v[56:57]
	v_pk_mov_b32 v[54:55], v[54:55], v[122:123] op_sel:[1,0]
	v_lshl_add_u64 v[132:133], v[102:103], 0, v[78:79]
	v_pk_add_f32 v[54:55], v[54:55], v[56:57]
	ds_bpermute_b32 v122, v71, v54
	v_lshl_add_u64 v[134:135], v[132:133], 0, s[46:47]
	v_lshl_add_u64 v[102:103], v[102:103], 0, v[80:81]
	s_waitcnt vmcnt(10)
	v_lshlrev_b32_e32 v124, 16, v39
	v_and_b32_e32 v125, 0xffff0000, v39
	s_waitcnt lgkmcnt(0)
	v_pk_add_f32 v[54:55], v[54:55], v[122:123]
	ds_bpermute_b32 v57, v71, v55
	ds_bpermute_b32 v56, v90, v54
	v_pk_mul_f32 v[130:131], v[124:125], v[124:125]
	v_lshlrev_b32_e32 v126, 16, v40
	v_and_b32_e32 v127, 0xffff0000, v40
	v_lshlrev_b32_e32 v128, 16, v41
	s_waitcnt lgkmcnt(0)
	v_pk_add_f32 v[54:55], v[54:55], v[56:57]
	ds_bpermute_b32 v57, v90, v55
	ds_bpermute_b32 v56, v91, v54
	v_and_b32_e32 v129, 0xffff0000, v41
	v_pk_mul_f32 v[40:41], v[126:127], v[126:127]
	s_waitcnt lgkmcnt(0)
	v_pk_add_f32 v[54:55], v[54:55], v[56:57]
	ds_bpermute_b32 v57, v91, v55
	ds_bpermute_b32 v56, v92, v54
	s_waitcnt lgkmcnt(0)
	v_pk_add_f32 v[54:55], v[54:55], v[56:57]
	s_nop 0
	v_pk_fma_f32 v[122:123], v[54:55], s[48:49], v[86:87] op_sel_hi:[1,0,0]
	s_nop 0
	v_mul_f32_e32 v54, 0x4b800000, v123
	v_cmp_gt_f32_e64 s[0:1], s76, v123
	v_cmp_gt_f32_e32 vcc, s76, v122
	s_nop 0
	v_cndmask_b32_e64 v54, v123, v54, s[0:1]
	v_rsq_f32_e32 v54, v54
	v_and_b32_e32 v123, 0xffff0000, v38
	v_mul_f32_e32 v55, 0x45800000, v54
	v_cndmask_b32_e64 v54, v54, v55, s[0:1]
	v_mul_f32_e32 v54, 0x3e0293ee, v54
	v_pk_mul_f32 v[56:57], v[54:55], v[104:105] op_sel_hi:[0,1]
	s_waitcnt vmcnt(0)
	v_pk_mul_f32 v[56:57], v[98:99], v[56:57]
	v_pk_mul_f32 v[98:99], v[54:55], v[108:109] op_sel_hi:[0,1]
	v_pk_mul_f32 v[98:99], v[100:101], v[98:99]
	v_pk_mul_f32 v[100:101], v[54:55], v[110:111] op_sel_hi:[0,1]
	v_pk_mul_f32 v[94:95], v[94:95], v[100:101]
	v_pk_mul_f32 v[100:101], v[54:55], v[112:113] op_sel_hi:[0,1]
	v_pk_mul_f32 v[96:97], v[96:97], v[100:101]
	v_pk_mul_f32 v[100:101], v[54:55], v[114:115] op_sel_hi:[0,1]
	v_pk_mul_f32 v[62:63], v[62:63], v[100:101]
	v_pk_mul_f32 v[100:101], v[54:55], v[116:117] op_sel_hi:[0,1]
	v_pk_mul_f32 v[64:65], v[100:101], v[64:65]
	v_pk_mul_f32 v[100:101], v[54:55], v[118:119] op_sel_hi:[0,1]
	v_pk_mul_f32 v[58:59], v[100:101], v[58:59]
	v_pk_mul_f32 v[100:101], v[54:55], v[120:121] op_sel_hi:[0,1]
	v_cvt_pk_bf16_f32 v54, v56, v57
	v_cvt_pk_bf16_f32 v56, v94, v95
	v_add_co_u32_e64 v94, s[0:1], s33, v132
	v_cvt_pk_bf16_f32 v55, v98, v99
	v_cvt_pk_bf16_f32 v57, v96, v97
	v_addc_co_u32_e64 v95, s[0:1], 0, v133, s[0:1]
	global_store_dwordx4 v[94:95], v[54:57], off offset:2048
	v_lshl_add_u64 v[94:95], v[102:103], 0, v[82:83]
	s_movk_i32 s0, 0x410
	v_cvt_pk_bf16_f32 v56, v58, v59
	v_pk_mul_f32 v[58:59], v[100:101], v[60:61]
	v_cvt_pk_bf16_f32 v54, v62, v63
	v_cvt_pk_bf16_f32 v55, v64, v65
	v_cvt_pk_bf16_f32 v57, v58, v59
	global_store_dwordx4 v[134:135], v[54:57], off offset:16
	s_nop 1
	v_mov_b64_e32 v[54:55], v[226:227]
	v_mov_b64_e32 v[56:57], v[228:229]
	s_nop 0
	s_nop 1
	v_mov_b64_e32 v[58:59], v[230:231]
	v_mov_b64_e32 v[60:61], v[232:233]
	v_mul_f32_e32 v62, 0x4b800000, v122
	v_cndmask_b32_e32 v62, v122, v62, vcc
	v_rsq_f32_e32 v62, v62
	v_lshlrev_b32_e32 v96, 16, v49
	v_and_b32_e32 v97, 0xffff0000, v49
	v_lshlrev_b32_e32 v98, 16, v42
	v_mul_f32_e32 v63, 0x45800000, v62
	v_cndmask_b32_e32 v62, v62, v63, vcc
; __device__ __forceinline__ void nsa_prep_tile(const Params& p, int pt, char* smem) {
;     ...
;         u16* qp = zr + 3072 + lane * 16;
;         float f[16];
;         unpack8(q0[r], f);
;         unpack8(q1[r], f + 8);
;         float ss = 0.f;
; #pragma unroll
;         for (int i = 0; i < 16; ++i) ss += f[i] * f[i];
;         ss += __shfl_xor(ss, 1); ss += __shfl_xor(ss, 2); ss += __shfl_xor(ss, 4);
;         float rr = rsqrtf(ss * (1.f / 128.f) + EPS) * (0.08838834764831845f * 1.4426950408889634f);
; #pragma unroll
;         for (int i = 0; i < 16; ++i) f[i] = f[i] * rr * qgp[i];
;         *(uint4*)qp = pack8(f);
;         *(uint4*)(qp + 8) = pack8(f + 8);
;     ...
;       {
;         u16* kp = zr + kcol + l5 * 8;
;         float f[8];
;         unpack8(kr[r], f);
;         float ss = 0.f;
; #pragma unroll
;         for (int i = 0; i < 8; ++i) ss += f[i] * f[i];
;         ss += __shfl_xor(ss, 1); ss += __shfl_xor(ss, 2); ss += __shfl_xor(ss, 4); ss += __shfl_xor(ss, 8);
;         float rr = rsqrtf(ss * (1.f / 128.f) + EPS);
; #pragma unroll
;         for (int i = 0; i < 8; ++i) f[i] = f[i] * rr * kgp[i];
;         *(uint4*)kp = pack8(f);
;         *(uint4*)(vt + tl * 520 + lane * 8) = (r == 0) ? vr0 : (r == 1) ? vr1 : (r == 2) ? vr2 : vr3;
	v_pk_mul_f32 v[64:65], v[62:63], v[136:137] op_sel_hi:[0,1]
	v_and_b32_e32 v99, 0xffff0000, v42
	v_lshlrev_b32_e32 v100, 16, v43
	v_and_b32_e32 v101, 0xffff0000, v43
	v_lshlrev_b32_e32 v102, 16, v44
	v_and_b32_e32 v103, 0xffff0000, v44
	v_lshlrev_b32_e32 v104, 16, v45
	v_and_b32_e32 v105, 0xffff0000, v45
	v_lshlrev_b32_e32 v122, 16, v38
	v_pk_mul_f32 v[114:115], v[98:99], v[98:99]
	v_pk_mul_f32 v[132:133], v[122:123], v[122:123]
	v_mov_b32_e32 v135, v114
	v_mov_b32_e32 v134, v132
	v_pk_mul_f32 v[112:113], v[100:101], v[100:101]
	v_mov_b32_e32 v114, v130
	v_pk_mul_f32 v[110:111], v[102:103], v[102:103]
	v_pk_mul_f32 v[38:39], v[128:129], v[128:129]
	v_pk_mul_f32 v[108:109], v[104:105], v[104:105]
	v_pk_mul_f32 v[58:59], v[58:59], v[64:65]
	v_pk_mul_f32 v[64:65], v[62:63], v[138:139] op_sel_hi:[0,1]
	v_pk_mul_f32 v[60:61], v[60:61], v[64:65]
	v_pk_mul_f32 v[64:65], v[62:63], v[140:141] op_sel_hi:[0,1]
	v_pk_mul_f32 v[64:65], v[54:55], v[64:65]
	v_pk_mul_f32 v[54:55], v[62:63], v[154:155] op_sel_hi:[0,1]
	v_pk_mul_f32 v[62:63], v[56:57], v[54:55]
	v_cvt_pk_bf16_f32 v54, v58, v59
	v_cvt_pk_bf16_f32 v55, v60, v61
	v_cvt_pk_bf16_f32 v56, v64, v65
	v_cvt_pk_bf16_f32 v57, v62, v63
	global_store_dwordx4 v[94:95], v[54:57], off
	v_lshlrev_b32_e32 v62, 16, v46
	v_and_b32_e32 v63, 0xffff0000, v46
	v_mad_u64_u32 v[54:55], s[0:1], v88, s0, v[76:77]
	ds_write_b128 v54, v[50:53]
	v_or_b32_e32 v50, 1, v88
	v_ashrrev_i32_e32 v51, 31, v50
	v_lshl_add_u64 v[50:51], v[50:51], 0, s[4:5]
	v_mad_u64_u32 v[60:61], s[0:1], v50, s77, v[84:85]
	v_mad_i32_i24 v61, v51, s77, v61
	v_lshlrev_b32_e32 v64, 16, v47
	v_and_b32_e32 v65, 0xffff0000, v47
	v_lshlrev_b32_e32 v94, 16, v48
	v_and_b32_e32 v95, 0xffff0000, v48
	s_nop 1
	v_mov_b64_e32 v[42:43], v[210:211]
	v_mov_b64_e32 v[44:45], v[212:213]
	s_nop 1
	v_mov_b64_e32 v[46:47], v[214:215]
	v_mov_b64_e32 v[48:49], v[216:217]
	s_nop 1
	v_mov_b64_e32 v[50:51], v[218:219]
	v_mov_b64_e32 v[52:53], v[220:221]
	s_nop 1
	v_mov_b64_e32 v[56:57], v[222:223]
	v_mov_b64_e32 v[58:59], v[224:225]
	v_pk_mul_f32 v[120:121], v[62:63], v[62:63]
	v_pk_mul_f32 v[118:119], v[64:65], v[64:65]
	v_add_f32_e32 v55, v120, v121
	v_add_f32_e32 v55, v55, v118
	v_pk_mul_f32 v[116:117], v[94:95], v[94:95]
	v_add_f32_e32 v55, v119, v55
	v_add_f32_e32 v55, v116, v55
	v_add_f32_e32 v106, v117, v55
	v_fmac_f32_e32 v106, v96, v96
	v_pk_fma_f32 v[116:117], v[96:97], v[96:97], v[106:107] op_sel_hi:[1,1,0]
	v_lshl_add_u64 v[118:119], v[60:61], 0, v[78:79]
	v_mov_b32_e32 v116, v133
	v_pk_add_f32 v[116:117], v[134:135], v[116:117]
	v_lshl_add_u64 v[120:121], v[118:119], 0, s[46:47]
	v_pk_add_f32 v[114:115], v[116:117], v[114:115]
	v_pk_mov_b32 v[116:117], v[130:131], v[112:113] op_sel:[1,0]
	v_mov_b32_e32 v112, v40
	v_pk_add_f32 v[114:115], v[116:117], v[114:115]
	v_pk_mov_b32 v[40:41], v[40:41], v[110:111] op_sel:[1,0]
	v_pk_add_f32 v[112:113], v[112:113], v[114:115]
	v_mov_b32_e32 v110, v38
	v_pk_add_f32 v[40:41], v[40:41], v[112:113]
	v_pk_mov_b32 v[38:39], v[38:39], v[108:109] op_sel:[1,0]
	v_pk_add_f32 v[40:41], v[110:111], v[40:41]
	v_lshl_add_u64 v[60:61], v[60:61], 0, v[80:81]
	v_pk_add_f32 v[38:39], v[38:39], v[40:41]
	ds_bpermute_b32 v108, v71, v38
	v_lshlrev_b32_e32 v110, 16, v24
	v_and_b32_e32 v111, 0xffff0000, v24
	v_lshlrev_b32_e32 v112, 16, v25
	v_and_b32_e32 v113, 0xffff0000, v25
	s_waitcnt lgkmcnt(0)
	v_pk_add_f32 v[38:39], v[38:39], v[108:109]
	ds_bpermute_b32 v41, v71, v39
	ds_bpermute_b32 v40, v90, v38
	v_pk_mul_f32 v[24:25], v[110:111], v[110:111]
	s_waitcnt lgkmcnt(0)
	v_pk_add_f32 v[38:39], v[38:39], v[40:41]
	ds_bpermute_b32 v41, v90, v39
	ds_bpermute_b32 v40, v91, v38
	s_waitcnt lgkmcnt(0)
	v_pk_add_f32 v[38:39], v[38:39], v[40:41]
	ds_bpermute_b32 v41, v91, v39
	ds_bpermute_b32 v40, v92, v38
	s_waitcnt lgkmcnt(0)
	v_pk_add_f32 v[38:39], v[38:39], v[40:41]
	s_nop 0
	v_pk_fma_f32 v[108:109], v[38:39], s[48:49], v[86:87] op_sel_hi:[1,0,0]
	s_nop 0
	v_mul_f32_e32 v38, 0x4b800000, v109
	v_cmp_gt_f32_e64 s[0:1], s76, v109
	v_cmp_gt_f32_e32 vcc, s76, v108
	s_nop 0
	v_cndmask_b32_e64 v38, v109, v38, s[0:1]
	v_rsq_f32_e32 v38, v38
	v_and_b32_e32 v109, 0xffff0000, v23
	v_mul_f32_e32 v39, 0x45800000, v38
	v_cndmask_b32_e64 v38, v38, v39, s[0:1]
	v_mul_f32_e32 v38, 0x3e0293ee, v38
	v_pk_mul_f32 v[40:41], v[38:39], v[62:63] op_sel_hi:[0,1]
	v_pk_mul_f32 v[40:41], v[56:57], v[40:41]
	v_pk_mul_f32 v[56:57], v[38:39], v[64:65] op_sel_hi:[0,1]
	v_pk_mul_f32 v[56:57], v[58:59], v[56:57]
	v_pk_mul_f32 v[58:59], v[38:39], v[94:95] op_sel_hi:[0,1]
	v_pk_mul_f32 v[50:51], v[50:51], v[58:59]
	v_pk_mul_f32 v[58:59], v[38:39], v[96:97] op_sel_hi:[0,1]
	v_pk_mul_f32 v[52:53], v[52:53], v[58:59]
	v_pk_mul_f32 v[58:59], v[38:39], v[98:99] op_sel_hi:[0,1]
	v_pk_mul_f32 v[46:47], v[46:47], v[58:59]
	v_pk_mul_f32 v[58:59], v[38:39], v[100:101] op_sel_hi:[0,1]
	v_pk_mul_f32 v[48:49], v[58:59], v[48:49]
	v_pk_mul_f32 v[58:59], v[38:39], v[102:103] op_sel_hi:[0,1]
	v_pk_mul_f32 v[42:43], v[58:59], v[42:43]
	v_pk_mul_f32 v[58:59], v[38:39], v[104:105] op_sel_hi:[0,1]
	v_cvt_pk_bf16_f32 v38, v40, v41
	v_cvt_pk_bf16_f32 v40, v50, v51
	v_add_co_u32_e64 v50, s[0:1], s33, v118
	v_cvt_pk_bf16_f32 v39, v56, v57
	v_cvt_pk_bf16_f32 v41, v52, v53
	v_addc_co_u32_e64 v51, s[0:1], 0, v119, s[0:1]
	global_store_dwordx4 v[50:51], v[38:41], off offset:2048
	v_lshl_add_u64 v[50:51], v[60:61], 0, v[82:83]
	v_lshlrev_b32_e32 v52, 16, v26
	v_cvt_pk_bf16_f32 v40, v42, v43
	v_pk_mul_f32 v[42:43], v[58:59], v[44:45]
	v_cvt_pk_bf16_f32 v38, v46, v47
	v_cvt_pk_bf16_f32 v39, v48, v49
	v_cvt_pk_bf16_f32 v41, v42, v43
	global_store_dwordx4 v[120:121], v[38:41], off offset:16
	s_nop 1
; __device__ __forceinline__ void nsa_prep_tile(const Params& p, int pt, char* smem) {
;     ...
;         u16* qp = zr + 3072 + lane * 16;
;         float f[16];
;         unpack8(q0[r], f);
;         unpack8(q1[r], f + 8);
;         float ss = 0.f;
; #pragma unroll
;         for (int i = 0; i < 16; ++i) ss += f[i] * f[i];
;         ss += __shfl_xor(ss, 1); ss += __shfl_xor(ss, 2); ss += __shfl_xor(ss, 4);
;         float rr = rsqrtf(ss * (1.f / 128.f) + EPS) * (0.08838834764831845f * 1.4426950408889634f);
; #pragma unroll
;         for (int i = 0; i < 16; ++i) f[i] = f[i] * rr * qgp[i];
;         *(uint4*)qp = pack8(f);
;         *(uint4*)(qp + 8) = pack8(f + 8);
;     ...
;       {
;         u16* kp = zr + kcol + l5 * 8;
;         float f[8];
;         unpack8(kr[r], f);
;         float ss = 0.f;
; #pragma unroll
;         for (int i = 0; i < 8; ++i) ss += f[i] * f[i];
;         ss += __shfl_xor(ss, 1); ss += __shfl_xor(ss, 2); ss += __shfl_xor(ss, 4); ss += __shfl_xor(ss, 8);
;         float rr = rsqrtf(ss * (1.f / 128.f) + EPS);
; #pragma unroll
;         for (int i = 0; i < 8; ++i) f[i] = f[i] * rr * kgp[i];
;         *(uint4*)kp = pack8(f);
;         *(uint4*)(vt + tl * 520 + lane * 8) = (r == 0) ? vr0 : (r == 1) ? vr1 : (r == 2) ? vr2 : vr3;
	v_mov_b64_e32 v[38:39], v[226:227]
	v_mov_b64_e32 v[40:41], v[228:229]
	s_nop 0
	s_nop 1
	v_mov_b64_e32 v[42:43], v[230:231]
	v_mov_b64_e32 v[44:45], v[232:233]
	v_mul_f32_e32 v46, 0x4b800000, v108
	v_cndmask_b32_e32 v46, v108, v46, vcc
	v_rsq_f32_e32 v46, v46
	ds_write_b128 v54, v[34:37] offset:1040
	v_or_b32_e32 v34, 2, v88
	v_ashrrev_i32_e32 v35, 31, v34
	v_mul_f32_e32 v47, 0x45800000, v46
	v_cndmask_b32_e32 v46, v46, v47, vcc
	v_pk_mul_f32 v[48:49], v[46:47], v[122:123] op_sel_hi:[0,1]
	v_lshl_add_u64 v[34:35], v[34:35], 0, s[4:5]
	v_and_b32_e32 v53, 0xffff0000, v26
	v_lshlrev_b32_e32 v56, 16, v27
	v_and_b32_e32 v57, 0xffff0000, v27
	v_lshlrev_b32_e32 v58, 16, v28
	v_and_b32_e32 v59, 0xffff0000, v28
	v_lshlrev_b32_e32 v60, 16, v29
	v_and_b32_e32 v61, 0xffff0000, v29
	v_lshlrev_b32_e32 v104, 16, v22
	v_and_b32_e32 v105, 0xffff0000, v22
	v_pk_mul_f32 v[96:97], v[52:53], v[52:53]
	v_lshlrev_b32_e32 v108, 16, v23
	v_pk_mul_f32 v[116:117], v[104:105], v[104:105]
	v_pk_mul_f32 v[114:115], v[108:109], v[108:109]
	v_mov_b32_e32 v118, v116
	v_mov_b32_e32 v119, v96
	v_pk_mul_f32 v[94:95], v[56:57], v[56:57]
	v_mov_b32_e32 v96, v114
	v_pk_mul_f32 v[64:65], v[58:59], v[58:59]
	v_pk_mul_f32 v[22:23], v[112:113], v[112:113]
	v_pk_mul_f32 v[62:63], v[60:61], v[60:61]
	v_pk_mul_f32 v[42:43], v[42:43], v[48:49]
	v_pk_mul_f32 v[48:49], v[46:47], v[124:125] op_sel_hi:[0,1]
	v_pk_mul_f32 v[44:45], v[44:45], v[48:49]
	v_pk_mul_f32 v[48:49], v[46:47], v[126:127] op_sel_hi:[0,1]
	v_pk_mul_f32 v[48:49], v[38:39], v[48:49]
	v_pk_mul_f32 v[38:39], v[46:47], v[128:129] op_sel_hi:[0,1]
	v_pk_mul_f32 v[46:47], v[40:41], v[38:39]
	v_cvt_pk_bf16_f32 v38, v42, v43
	v_cvt_pk_bf16_f32 v39, v44, v45
	v_cvt_pk_bf16_f32 v40, v48, v49
	v_cvt_pk_bf16_f32 v41, v46, v47
	global_store_dwordx4 v[50:51], v[38:41], off
	v_mad_u64_u32 v[42:43], s[0:1], v34, s77, v[84:85]
	v_mad_i32_i24 v43, v35, s77, v43
	v_lshlrev_b32_e32 v44, 16, v30
	v_and_b32_e32 v45, 0xffff0000, v30
	v_lshlrev_b32_e32 v46, 16, v31
	v_and_b32_e32 v47, 0xffff0000, v31
	v_lshlrev_b32_e32 v48, 16, v32
	v_and_b32_e32 v49, 0xffff0000, v32
	v_lshlrev_b32_e32 v50, 16, v33
	v_and_b32_e32 v51, 0xffff0000, v33
	s_nop 1
	v_mov_b64_e32 v[26:27], v[210:211]
	v_mov_b64_e32 v[28:29], v[212:213]
	s_nop 1
	v_mov_b64_e32 v[30:31], v[214:215]
	v_mov_b64_e32 v[32:33], v[216:217]
	s_nop 1
	v_mov_b64_e32 v[34:35], v[218:219]
	v_mov_b64_e32 v[36:37], v[220:221]
	s_nop 1
	v_mov_b64_e32 v[38:39], v[222:223]
	v_mov_b64_e32 v[40:41], v[224:225]
	v_pk_mul_f32 v[102:103], v[44:45], v[44:45]
	v_pk_mul_f32 v[100:101], v[46:47], v[46:47]
	v_add_f32_e32 v55, v102, v103
	v_add_f32_e32 v55, v55, v100
	v_pk_mul_f32 v[98:99], v[48:49], v[48:49]
	v_add_f32_e32 v55, v101, v55
	v_add_f32_e32 v55, v98, v55
	v_add_f32_e32 v98, v99, v55
	v_fmac_f32_e32 v98, v50, v50
	v_pk_fma_f32 v[98:99], v[50:51], v[50:51], v[98:99] op_sel_hi:[1,1,0]
	v_lshl_add_u64 v[100:101], v[42:43], 0, v[78:79]
	v_mov_b32_e32 v98, v117
	v_pk_add_f32 v[98:99], v[118:119], v[98:99]
	v_lshl_add_u64 v[102:103], v[100:101], 0, s[46:47]
	v_pk_add_f32 v[96:97], v[98:99], v[96:97]
	v_pk_mov_b32 v[98:99], v[114:115], v[94:95] op_sel:[1,0]
	v_mov_b32_e32 v94, v24
	v_pk_add_f32 v[96:97], v[98:99], v[96:97]
	v_pk_mov_b32 v[24:25], v[24:25], v[64:65] op_sel:[1,0]
	v_pk_add_f32 v[94:95], v[94:95], v[96:97]
	v_mov_b32_e32 v64, v22
	v_pk_add_f32 v[24:25], v[24:25], v[94:95]
	v_pk_mov_b32 v[22:23], v[22:23], v[62:63] op_sel:[1,0]
	v_pk_add_f32 v[24:25], v[64:65], v[24:25]
	v_lshl_add_u64 v[42:43], v[42:43], 0, v[80:81]
	v_pk_add_f32 v[22:23], v[22:23], v[24:25]
	ds_bpermute_b32 v62, v71, v22
	s_waitcnt lgkmcnt(0)
	v_pk_add_f32 v[22:23], v[22:23], v[62:63]
	ds_bpermute_b32 v25, v71, v23
	ds_bpermute_b32 v24, v90, v22
	s_waitcnt lgkmcnt(0)
	v_pk_add_f32 v[22:23], v[22:23], v[24:25]
	ds_bpermute_b32 v25, v90, v23
	ds_bpermute_b32 v24, v91, v22
	s_waitcnt lgkmcnt(0)
	v_pk_add_f32 v[22:23], v[22:23], v[24:25]
	ds_bpermute_b32 v25, v91, v23
	ds_bpermute_b32 v24, v92, v22
	s_waitcnt lgkmcnt(0)
	v_pk_add_f32 v[22:23], v[22:23], v[24:25]
	s_nop 0
	v_pk_fma_f32 v[62:63], v[22:23], s[48:49], v[86:87] op_sel_hi:[1,0,0]
	s_nop 0
	v_mul_f32_e32 v22, 0x4b800000, v63
	v_cmp_gt_f32_e64 s[0:1], s76, v63
	v_cmp_gt_f32_e32 vcc, s76, v62
	s_nop 0
	v_cndmask_b32_e64 v22, v63, v22, s[0:1]
	v_rsq_f32_e32 v22, v22
	s_nop 0
	v_mul_f32_e32 v23, 0x45800000, v22
	v_cndmask_b32_e64 v22, v22, v23, s[0:1]
	v_mul_f32_e32 v22, 0x3e0293ee, v22
	v_pk_mul_f32 v[24:25], v[22:23], v[44:45] op_sel_hi:[0,1]
	v_lshlrev_b32_e32 v44, 16, v15
	v_and_b32_e32 v45, 0xffff0000, v15
	v_pk_mul_f32 v[24:25], v[38:39], v[24:25]
	v_pk_mul_f32 v[38:39], v[22:23], v[46:47] op_sel_hi:[0,1]
	v_pk_mul_f32 v[38:39], v[40:41], v[38:39]
	v_pk_mul_f32 v[40:41], v[22:23], v[48:49] op_sel_hi:[0,1]
	v_pk_mul_f32 v[34:35], v[34:35], v[40:41]
	v_pk_mul_f32 v[40:41], v[22:23], v[50:51] op_sel_hi:[0,1]
	v_pk_mul_f32 v[36:37], v[36:37], v[40:41]
	v_pk_mul_f32 v[40:41], v[22:23], v[52:53] op_sel_hi:[0,1]
	v_pk_mul_f32 v[30:31], v[30:31], v[40:41]
	v_pk_mul_f32 v[40:41], v[22:23], v[56:57] op_sel_hi:[0,1]
	v_pk_mul_f32 v[32:33], v[40:41], v[32:33]
	v_pk_mul_f32 v[40:41], v[22:23], v[58:59] op_sel_hi:[0,1]
	v_pk_mul_f32 v[26:27], v[40:41], v[26:27]
	v_pk_mul_f32 v[40:41], v[22:23], v[60:61] op_sel_hi:[0,1]
	v_cvt_pk_bf16_f32 v22, v24, v25
	v_cvt_pk_bf16_f32 v24, v34, v35
	v_add_co_u32_e64 v34, s[0:1], s33, v100
	v_cvt_pk_bf16_f32 v23, v38, v39
	v_cvt_pk_bf16_f32 v25, v36, v37
	v_addc_co_u32_e64 v35, s[0:1], 0, v101, s[0:1]
	global_store_dwordx4 v[34:35], v[22:25], off offset:2048
	v_lshl_add_u64 v[34:35], v[42:43], 0, v[82:83]
	v_lshlrev_b32_e32 v42, 16, v14
; __device__ __forceinline__ void nsa_prep_tile(const Params& p, int pt, char* smem) {
;     ...
;   for (int r0 = 0; r0 < 8; r0 += 4) {
;     uint4 q0[4], q1[4], kr[4];
;     uint4 vr0, vr1, vr2, vr3;
; #pragma unroll
;     for (int r = 0; r < 4; ++r) {
;       const u16* zr = Z + (tok0 + wid * 8 + r0 + r) * LDZ0;
;       q0[r] = *(const uint4*)(zr + 3072 + lane * 16);
;       q1[r] = *(const uint4*)(zr + 3072 + lane * 16 + 8);
;       kr[r] = *(const uint4*)(zr + kcol + l5 * 8);
;     }
;     {
;       const u16* zv = Z + (tok0 + wid * 8 + r0) * LDZ0 + vcol + l5 * 8;
;       vr0 = *(const uint4*)zv;
;       vr1 = *(const uint4*)(zv + LDZ0);
;       vr2 = *(const uint4*)(zv + 2 * LDZ0);
;       vr3 = *(const uint4*)(zv + 3 * LDZ0);
;     }
; #pragma unroll
;     ...
;       {
;         u16* kp = zr + kcol + l5 * 8;
;         float f[8];
;         unpack8(kr[r], f);
;         float ss = 0.f;
; #pragma unroll
;         for (int i = 0; i < 8; ++i) ss += f[i] * f[i];
;         ss += __shfl_xor(ss, 1); ss += __shfl_xor(ss, 2); ss += __shfl_xor(ss, 4); ss += __shfl_xor(ss, 8);
;         float rr = rsqrtf(ss * (1.f / 128.f) + EPS);
; #pragma unroll
;         for (int i = 0; i < 8; ++i) f[i] = f[i] * rr * kgp[i];
;         *(uint4*)kp = pack8(f);
;         *(uint4*)(vt + tl * 520 + lane * 8) = (r == 0) ? vr0 : (r == 1) ? vr1 : (r == 2) ? vr2 : vr3;
	v_cvt_pk_bf16_f32 v24, v26, v27
	v_pk_mul_f32 v[26:27], v[40:41], v[28:29]
	v_cvt_pk_bf16_f32 v22, v30, v31
	v_cvt_pk_bf16_f32 v23, v32, v33
	v_cvt_pk_bf16_f32 v25, v26, v27
	global_store_dwordx4 v[102:103], v[22:25], off offset:16
	s_nop 1
	v_mov_b64_e32 v[22:23], v[226:227]
	v_mov_b64_e32 v[24:25], v[228:229]
	s_nop 0
	s_nop 1
	v_mov_b64_e32 v[26:27], v[230:231]
	v_mov_b64_e32 v[28:29], v[232:233]
	v_mul_f32_e32 v30, 0x4b800000, v62
	v_cndmask_b32_e32 v30, v62, v30, vcc
	v_rsq_f32_e32 v30, v30
	ds_write_b128 v54, v[18:21] offset:2080
	v_or_b32_e32 v18, 3, v88
	v_ashrrev_i32_e32 v19, 31, v18
	v_mul_f32_e32 v31, 0x45800000, v30
	v_cndmask_b32_e32 v30, v30, v31, vcc
	v_pk_mul_f32 v[32:33], v[30:31], v[104:105] op_sel_hi:[0,1]
	v_lshl_add_u64 v[18:19], v[18:19], 0, s[4:5]
	v_and_b32_e32 v43, 0xffff0000, v14
	v_lshlrev_b32_e32 v46, 16, v16
	v_and_b32_e32 v47, 0xffff0000, v16
	v_lshlrev_b32_e32 v48, 16, v17
	v_and_b32_e32 v49, 0xffff0000, v17
	v_lshlrev_b32_e32 v50, 16, v10
	v_and_b32_e32 v51, 0xffff0000, v10
	v_lshlrev_b32_e32 v52, 16, v11
	v_and_b32_e32 v53, 0xffff0000, v11
	v_lshlrev_b32_e32 v56, 16, v12
	v_and_b32_e32 v57, 0xffff0000, v12
	v_lshlrev_b32_e32 v58, 16, v13
	v_and_b32_e32 v59, 0xffff0000, v13
	v_pk_mul_f32 v[64:65], v[50:51], v[50:51]
	v_pk_mul_f32 v[62:63], v[52:53], v[52:53]
	v_mov_b32_e32 v99, v64
	v_pk_mul_f32 v[60:61], v[56:57], v[56:57]
	v_pk_mul_f32 v[38:39], v[58:59], v[58:59]
	v_pk_mul_f32 v[26:27], v[26:27], v[32:33]
	v_pk_mul_f32 v[32:33], v[30:31], v[108:109] op_sel_hi:[0,1]
	v_pk_mul_f32 v[28:29], v[28:29], v[32:33]
	v_pk_mul_f32 v[32:33], v[30:31], v[110:111] op_sel_hi:[0,1]
	v_pk_mul_f32 v[32:33], v[22:23], v[32:33]
	v_pk_mul_f32 v[22:23], v[30:31], v[112:113] op_sel_hi:[0,1]
	v_pk_mul_f32 v[30:31], v[24:25], v[22:23]
	v_cvt_pk_bf16_f32 v22, v26, v27
	v_cvt_pk_bf16_f32 v23, v28, v29
	v_cvt_pk_bf16_f32 v24, v32, v33
	v_cvt_pk_bf16_f32 v25, v30, v31
	global_store_dwordx4 v[34:35], v[22:25], off
	v_mad_u64_u32 v[26:27], s[0:1], v18, s77, v[84:85]
	v_mad_i32_i24 v27, v19, s77, v27
	s_nop 1
	v_mov_b64_e32 v[10:11], v[210:211]
	v_mov_b64_e32 v[12:13], v[212:213]
	s_nop 1
	v_mov_b64_e32 v[14:15], v[214:215]
	v_mov_b64_e32 v[16:17], v[216:217]
	s_nop 1
	v_mov_b64_e32 v[18:19], v[218:219]
	v_mov_b64_e32 v[20:21], v[220:221]
	s_nop 1
	v_mov_b64_e32 v[22:23], v[222:223]
	v_mov_b64_e32 v[24:25], v[224:225]
	v_pk_mul_f32 v[32:33], v[42:43], v[42:43]
	v_pk_mul_f32 v[30:31], v[44:45], v[44:45]
	v_add_f32_e32 v32, v32, v33
	v_add_f32_e32 v30, v32, v30
	v_pk_mul_f32 v[28:29], v[46:47], v[46:47]
	v_add_f32_e32 v30, v31, v30
	v_add_f32_e32 v28, v28, v30
	v_add_f32_e32 v28, v29, v28
	v_fmac_f32_e32 v28, v48, v48
	v_pk_fma_f32 v[88:89], v[48:49], v[48:49], v[28:29] op_sel_hi:[1,1,0]
	v_lshlrev_b32_e32 v28, 16, v6
	v_and_b32_e32 v29, 0xffff0000, v6
	v_lshlrev_b32_e32 v30, 16, v7
	v_and_b32_e32 v31, 0xffff0000, v7
	v_pk_mul_f32 v[96:97], v[28:29], v[28:29]
	v_pk_mul_f32 v[94:95], v[30:31], v[30:31]
	v_mov_b32_e32 v98, v96
	v_mov_b32_e32 v88, v97
	v_lshlrev_b32_e32 v32, 16, v8
	v_and_b32_e32 v33, 0xffff0000, v8
	v_pk_add_f32 v[88:89], v[98:99], v[88:89]
	v_mov_b32_e32 v64, v94
	v_lshlrev_b32_e32 v34, 16, v9
	v_and_b32_e32 v35, 0xffff0000, v9
	v_pk_mul_f32 v[8:9], v[32:33], v[32:33]
	v_pk_add_f32 v[64:65], v[88:89], v[64:65]
	v_pk_mov_b32 v[88:89], v[94:95], v[62:63] op_sel:[1,0]
	v_mov_b32_e32 v62, v8
	v_pk_add_f32 v[64:65], v[88:89], v[64:65]
	v_pk_mul_f32 v[6:7], v[34:35], v[34:35]
	v_pk_add_f32 v[62:63], v[62:63], v[64:65]
	v_pk_mov_b32 v[8:9], v[8:9], v[60:61] op_sel:[1,0]
	v_mov_b32_e32 v60, v6
	v_pk_add_f32 v[8:9], v[8:9], v[62:63]
	v_pk_mov_b32 v[6:7], v[6:7], v[38:39] op_sel:[1,0]
	v_pk_add_f32 v[8:9], v[60:61], v[8:9]
	v_lshl_add_u64 v[40:41], v[26:27], 0, v[78:79]
	v_pk_add_f32 v[6:7], v[6:7], v[8:9]
	ds_bpermute_b32 v38, v71, v6
	v_lshl_add_u64 v[36:37], v[40:41], 0, s[46:47]
	v_lshl_add_u64 v[26:27], v[26:27], 0, v[80:81]
	s_waitcnt lgkmcnt(0)
	v_pk_add_f32 v[6:7], v[6:7], v[38:39]
	ds_bpermute_b32 v9, v71, v7
	ds_bpermute_b32 v8, v90, v6
	s_waitcnt lgkmcnt(0)
	v_pk_add_f32 v[6:7], v[6:7], v[8:9]
	ds_bpermute_b32 v9, v90, v7
	ds_bpermute_b32 v8, v91, v6
	s_waitcnt lgkmcnt(0)
	v_pk_add_f32 v[6:7], v[6:7], v[8:9]
	ds_bpermute_b32 v9, v91, v7
	ds_bpermute_b32 v8, v92, v6
	s_waitcnt lgkmcnt(0)
	v_pk_add_f32 v[6:7], v[6:7], v[8:9]
	s_nop 0
	v_pk_fma_f32 v[38:39], v[6:7], s[48:49], v[86:87] op_sel_hi:[1,0,0]
	s_nop 0
	v_mul_f32_e32 v6, 0x4b800000, v39
	v_cmp_gt_f32_e64 s[0:1], s76, v39
	v_cmp_gt_f32_e32 vcc, s76, v38
	s_nop 0
	v_cndmask_b32_e64 v6, v39, v6, s[0:1]
	v_rsq_f32_e32 v6, v6
	s_nop 0
	v_mul_f32_e32 v7, 0x45800000, v6
	v_cndmask_b32_e64 v6, v6, v7, s[0:1]
	v_mul_f32_e32 v6, 0x3e0293ee, v6
	v_pk_mul_f32 v[8:9], v[6:7], v[42:43] op_sel_hi:[0,1]
	v_pk_mul_f32 v[8:9], v[22:23], v[8:9]
	v_pk_mul_f32 v[22:23], v[6:7], v[44:45] op_sel_hi:[0,1]
	v_pk_mul_f32 v[22:23], v[24:25], v[22:23]
	v_pk_mul_f32 v[24:25], v[6:7], v[46:47] op_sel_hi:[0,1]
	v_pk_mul_f32 v[24:25], v[18:19], v[24:25]
	v_pk_mul_f32 v[18:19], v[6:7], v[48:49] op_sel_hi:[0,1]
	v_pk_mul_f32 v[20:21], v[20:21], v[18:19]
	v_pk_mul_f32 v[18:19], v[6:7], v[50:51] op_sel_hi:[0,1]
	v_pk_mul_f32 v[14:15], v[14:15], v[18:19]
	v_pk_mul_f32 v[18:19], v[6:7], v[52:53] op_sel_hi:[0,1]
	v_pk_mul_f32 v[16:17], v[18:19], v[16:17]
	v_pk_mul_f32 v[18:19], v[6:7], v[56:57] op_sel_hi:[0,1]
	v_pk_mul_f32 v[18:19], v[18:19], v[10:11]
	v_pk_mul_f32 v[10:11], v[6:7], v[58:59] op_sel_hi:[0,1]
	v_cvt_pk_bf16_f32 v6, v8, v9
	v_cvt_pk_bf16_f32 v9, v20, v21
	v_add_co_u32_e64 v20, s[0:1], s33, v40
	v_cvt_pk_bf16_f32 v7, v22, v23
	v_cvt_pk_bf16_f32 v8, v24, v25
	v_addc_co_u32_e64 v21, s[0:1], 0, v41, s[0:1]
	v_pk_mul_f32 v[10:11], v[10:11], v[12:13]
	global_store_dwordx4 v[20:21], v[6:9], off offset:2048
	s_mov_b32 s0, 4
	s_nop 0
	v_cvt_pk_bf16_f32 v6, v14, v15
	v_cvt_pk_bf16_f32 v7, v16, v17
	v_cvt_pk_bf16_f32 v8, v18, v19
	v_cvt_pk_bf16_f32 v9, v10, v11
	global_store_dwordx4 v[36:37], v[6:9], off offset:16
	s_nop 1
	v_mov_b64_e32 v[6:7], v[226:227]
	v_mov_b64_e32 v[8:9], v[228:229]
	s_nop 0
	s_nop 1
	v_mov_b64_e32 v[10:11], v[230:231]
	v_mov_b64_e32 v[12:13], v[232:233]
	v_mul_f32_e32 v14, 0x4b800000, v38
	v_cndmask_b32_e32 v14, v38, v14, vcc
	v_rsq_f32_e32 v14, v14
	v_lshl_add_u64 v[18:19], v[26:27], 0, v[82:83]
	ds_write_b128 v54, v[2:5] offset:3120
	v_mul_f32_e32 v15, 0x45800000, v14
	v_cndmask_b32_e32 v14, v14, v15, vcc
	v_pk_mul_f32 v[16:17], v[14:15], v[28:29] op_sel_hi:[0,1]
	s_and_b64 vcc, exec, s[6:7]
	s_mov_b64 s[6:7], 0
	v_pk_mul_f32 v[10:11], v[10:11], v[16:17]
	v_pk_mul_f32 v[16:17], v[14:15], v[30:31] op_sel_hi:[0,1]
	v_pk_mul_f32 v[12:13], v[12:13], v[16:17]
	v_pk_mul_f32 v[16:17], v[14:15], v[32:33] op_sel_hi:[0,1]
	v_pk_mul_f32 v[16:17], v[6:7], v[16:17]
	v_pk_mul_f32 v[6:7], v[14:15], v[34:35] op_sel_hi:[0,1]
	v_pk_mul_f32 v[14:15], v[8:9], v[6:7]
	v_cvt_pk_bf16_f32 v6, v10, v11
	v_cvt_pk_bf16_f32 v7, v12, v13
	v_cvt_pk_bf16_f32 v8, v16, v17
	v_cvt_pk_bf16_f32 v9, v14, v15
	global_store_dwordx4 v[18:19], v[6:9], off
	s_cbranch_vccnz .LBB0_183
; __device__ __forceinline__ void nsa_prep_tile(const Params& p, int pt, char* smem) {
;     ...
;   __syncthreads();
;   {
;     const int r = tid, br = r >> 8, kvh = (r >> 7) & 1, d = r & 127;
;     const int b = pt >> 5, kb0 = (pt & 31) * 2;
;     u16* dst = (br ? p.VWT : p.VST) + ((long)((b * 2 + kvh) * 64 + kb0)) * 4096 + d * 32;
; #pragma unroll
;     for (int hb = 0; hb < 2; ++hb) {
; #pragma unroll
;       for (int fq_ = 0; fq_ < 4; ++fq_) {
;         unsigned w[4];
; #pragma unroll
;         for (int i = 0; i < 4; ++i) {
;           const int a = i >> 1, ii = (i & 1) * 2;
;           const int key = hb * 32 + a * 16 + fq_ * 4 + ii;
;           unsigned lo = vt[key * 520 + r], hi = vt[(key + 1) * 520 + r];
;           w[i] = lo | (hi << 16);
;         }
;         uint4 o;
;         o.x = w[0]; o.y = w[1]; o.z = w[2]; o.w = w[3];
;         *(uint4*)(dst + hb * 4096 + fq_ * 8) = o;
;       }
;     }
;   }
;   __syncthreads();
	s_lshr_b32 s0, s2, 4
	v_readlane_b32 s16, v248, 10
	s_and_b32 s0, s0, 30
	v_lshrrev_b32_e32 v4, 7, v1
	v_readlane_b32 s27, v248, 21
	v_readlane_b32 s29, v248, 23
	v_readlane_b32 s26, v248, 20
	v_readlane_b32 s28, v248, 22
	v_mov_b32_e32 v2, s29
	v_mov_b32_e32 v3, s27
	v_cmp_gt_u32_e32 vcc, s3, v1
	v_and_or_b32 v4, v4, 1, s0
	s_lshl_b32 s0, s8, 14
	v_cndmask_b32_e32 v3, v2, v3, vcc
	v_mov_b32_e32 v2, s28
	v_mov_b32_e32 v5, s26
	s_and_b32 s0, s0, 0x7c000
	v_cndmask_b32_e32 v2, v2, v5, vcc
	v_lshl_or_b32 v4, v4, 19, s0
	v_mov_b32_e32 v5, v0
	v_lshl_add_u64 v[2:3], v[2:3], 0, v[4:5]
	v_and_b32_e32 v4, 0x1fc0, v77
	v_lshl_add_u32 v1, v1, 1, 0
	s_waitcnt lgkmcnt(0)
	s_barrier
	v_lshl_add_u64 v[2:3], v[2:3], 0, v[4:5]
	ds_read_u16 v4, v1
	ds_read_u16 v5, v1 offset:1040
	ds_read_u16 v6, v1 offset:2080
	ds_read_u16 v7, v1 offset:3120
	ds_read_u16 v8, v1 offset:4160
	ds_read_u16 v9, v1 offset:5200
	ds_read_u16 v10, v1 offset:6240
	ds_read_u16 v11, v1 offset:7280
	s_waitcnt lgkmcnt(6)
	v_lshl_or_b32 v4, v5, 16, v4
	s_waitcnt lgkmcnt(4)
	v_lshl_or_b32 v5, v7, 16, v6
	ds_read_u16 v6, v1 offset:16640
	ds_read_u16 v7, v1 offset:17680
	ds_read_u16 v12, v1 offset:18720
	ds_read_u16 v13, v1 offset:19760
	ds_read_u16 v14, v1 offset:20800
	ds_read_u16 v15, v1 offset:21840
	ds_read_u16 v16, v1 offset:22880
	ds_read_u16 v17, v1 offset:23920
	s_waitcnt lgkmcnt(6)
	v_lshl_or_b32 v6, v7, 16, v6
	s_waitcnt lgkmcnt(4)
	v_lshl_or_b32 v7, v13, 16, v12
	global_store_dwordx4 v[2:3], v[4:7], off
	s_mov_b64 s[0:1], 0
	v_readlane_b32 s17, v248, 11
	v_lshl_or_b32 v4, v9, 16, v8
	v_lshl_or_b32 v5, v11, 16, v10
	s_waitcnt lgkmcnt(2)
	v_lshl_or_b32 v6, v15, 16, v14
	s_waitcnt lgkmcnt(0)
	v_lshl_or_b32 v7, v17, 16, v16
	global_store_dwordx4 v[2:3], v[4:7], off offset:16
	ds_read_u16 v4, v1 offset:8320
	ds_read_u16 v5, v1 offset:9360
	ds_read_u16 v6, v1 offset:10400
	ds_read_u16 v7, v1 offset:11440
	ds_read_u16 v8, v1 offset:12480
	ds_read_u16 v9, v1 offset:13520
	ds_read_u16 v10, v1 offset:14560
	ds_read_u16 v11, v1 offset:15600
	s_waitcnt lgkmcnt(6)
	v_lshl_or_b32 v4, v5, 16, v4
	s_waitcnt lgkmcnt(4)
	v_lshl_or_b32 v5, v7, 16, v6
	ds_read_u16 v6, v1 offset:24960
	ds_read_u16 v7, v1 offset:26000
	ds_read_u16 v12, v1 offset:27040
	ds_read_u16 v13, v1 offset:28080
	ds_read_u16 v14, v1 offset:29120
	ds_read_u16 v15, v1 offset:30160
	ds_read_u16 v16, v1 offset:31200
	ds_read_u16 v17, v1 offset:32240
	s_waitcnt lgkmcnt(6)
	v_lshl_or_b32 v6, v7, 16, v6
	s_waitcnt lgkmcnt(4)
	v_lshl_or_b32 v7, v13, 16, v12
	global_store_dwordx4 v[2:3], v[4:7], off offset:32
	v_readlane_b32 s18, v248, 12
	v_readlane_b32 s19, v248, 13
	v_lshl_or_b32 v4, v9, 16, v8
	v_lshl_or_b32 v5, v11, 16, v10
	s_waitcnt lgkmcnt(2)
	v_lshl_or_b32 v6, v15, 16, v14
	s_waitcnt lgkmcnt(0)
	v_lshl_or_b32 v7, v17, 16, v16
	global_store_dwordx4 v[2:3], v[4:7], off offset:48
	ds_read_u16 v4, v1 offset:33280
	ds_read_u16 v5, v1 offset:34320
	ds_read_u16 v6, v1 offset:35360
	ds_read_u16 v7, v1 offset:36400
	ds_read_u16 v10, v1 offset:37440
	ds_read_u16 v11, v1 offset:38480
	ds_read_u16 v12, v1 offset:39520
	ds_read_u16 v13, v1 offset:40560
	s_waitcnt lgkmcnt(6)
	v_lshl_or_b32 v4, v5, 16, v4
	s_waitcnt lgkmcnt(4)
	v_lshl_or_b32 v5, v7, 16, v6
	ds_read_u16 v6, v1 offset:49920
	ds_read_u16 v7, v1 offset:50960
	ds_read_u16 v8, v1 offset:52000
	ds_read_u16 v9, v1 offset:53040
	ds_read_u16 v14, v1 offset:54080
	ds_read_u16 v15, v1 offset:55120
	ds_read_u16 v16, v1 offset:56160
	ds_read_u16 v17, v1 offset:57200
	s_waitcnt lgkmcnt(6)
	v_lshl_or_b32 v6, v7, 16, v6
	s_waitcnt lgkmcnt(4)
	v_lshl_or_b32 v7, v9, 16, v8
	v_add_co_u32_e32 v8, vcc, s12, v2
	v_lshl_or_b32 v2, v11, 16, v10
	s_nop 0
	v_addc_co_u32_e32 v9, vcc, 0, v3, vcc
	global_store_dwordx4 v[8:9], v[4:7], off
	v_lshl_or_b32 v3, v13, 16, v12
	v_readlane_b32 s20, v248, 14
	s_waitcnt lgkmcnt(2)
	v_lshl_or_b32 v4, v15, 16, v14
	s_waitcnt lgkmcnt(0)
	v_lshl_or_b32 v5, v17, 16, v16
	global_store_dwordx4 v[8:9], v[2:5], off offset:16
	ds_read_u16 v2, v1 offset:41600
	ds_read_u16 v3, v1 offset:42640
	ds_read_u16 v4, v1 offset:43680
	ds_read_u16 v5, v1 offset:44720
	ds_read_u16 v6, v1 offset:45760
	ds_read_u16 v7, v1 offset:46800
	ds_read_u16 v10, v1 offset:47840
	ds_read_u16 v11, v1 offset:48880
	s_waitcnt lgkmcnt(6)
	v_lshl_or_b32 v2, v3, 16, v2
	s_waitcnt lgkmcnt(4)
	v_lshl_or_b32 v3, v5, 16, v4
	ds_read_u16 v4, v1 offset:58240
	ds_read_u16 v5, v1 offset:59280
	ds_read_u16 v12, v1 offset:60320
	ds_read_u16 v13, v1 offset:61360
	ds_read_u16 v14, v1 offset:62400
	ds_read_u16 v15, v1 offset:63440
	ds_read_u16 v16, v1 offset:64480
	ds_read_u16 v1, v1 offset:65520
	s_waitcnt lgkmcnt(6)
	v_lshl_or_b32 v4, v5, 16, v4
	s_waitcnt lgkmcnt(4)
	v_lshl_or_b32 v5, v13, 16, v12
	global_store_dwordx4 v[8:9], v[2:5], off offset:32
	v_readlane_b32 s21, v248, 15
	v_readlane_b32 s22, v248, 16
	v_lshl_or_b32 v2, v7, 16, v6
	v_lshl_or_b32 v3, v11, 16, v10
	s_waitcnt lgkmcnt(2)
	v_lshl_or_b32 v4, v15, 16, v14
	s_waitcnt lgkmcnt(0)
	v_lshl_or_b32 v5, v1, 16, v16
	v_readlane_b32 s23, v248, 17
	v_readlane_b32 s24, v248, 18
	v_readlane_b32 s25, v248, 19
	v_readlane_b32 s30, v248, 24
	v_readlane_b32 s31, v248, 25
	global_store_dwordx4 v[8:9], v[2:5], off offset:48
	s_barrier

; #define BAR __builtin_amdgcn_s_barrier()
;     ...
;   for (int vw = blockIdx.x; vw < nwg; vw += gridDim.x) {
;     int tid_ = threadIdx.x;
;     asm volatile("" : "+v"(tid_));
;     const int wid = tid_ >> 6, lane = tid_ & 63, wr = wid >> 2, wc = wid & 3, fr = lane & 15, fq = lane >> 4;
;     int brow, bcol;
;     TILE_COORDS(vw, brow, bcol);
;     f32x4 acc[2][2][4][2] = {};
;     bf16x8 At[4][2], B0[2][2], B1[2][2];
;     STAGE(SB(0, 0), Bt, bcol, 0); STAGE(SA(0, 0), A, brow, 0);
;     STAGE(SB(0, 1), Bt, bcol + HALF, 0); STAGE(SA(0, 1), A, brow + HALF, 0);
;     if (wr == 1) BAR;
.LBB0_432:
	v_ashrrev_i32_e32 v0, 31, v152
	s_add_i32 s16, s19, s16
	v_lshrrev_b32_e32 v0, 26, v0
	s_ashr_i32 s17, s16, 31
	v_add_u32_e32 v0, v152, v0
	s_lshr_b32 s17, s17, 27
	v_ashrrev_i32_e32 v1, 6, v0
	v_bfe_i32 v0, v152, 27, 1
	s_add_i32 s18, s16, s17
	v_lshlrev_b32_e32 v20, 4, v152
	v_lshrrev_b32_e32 v0, 22, v0
	s_and_b32 s17, s18, 0xffe0
	v_add_u32_e32 v0, v20, v0
	s_sub_i32 s16, s16, s17
	v_and_b32_e32 v0, 0xfffffc00, v0
	s_bfe_i32 s17, s16, 0x80000
	v_sub_u32_e32 v0, v20, v0
	s_bfe_u32 s17, s17, 0x2000d
	v_lshrrev_b32_e32 v2, 4, v0
	s_add_i32 s17, s16, s17
	v_bitop3_b32 v2, v2, v0, 32 bitop3:0x6c
	s_bfe_i32 s19, s17, 0x80000
	v_ashrrev_i32_e32 v3, 31, v2
	s_sext_i32_i16 s19, s19
	v_lshrrev_b32_e32 v3, 26, v3
	s_lshr_b32 s37, s19, 2
	s_and_b32 s17, s17, 0xfc
	v_add_u32_e32 v3, v2, v3
	s_sub_i32 s16, s16, s17
	s_lshl_b32 s20, s37, 8
	v_lshlrev_b32_e32 v0, 3, v1
	v_ashrrev_i32_e32 v4, 6, v3
	v_and_b32_e32 v3, 0xc0, v3
	s_sext_i32_i8 s16, s16
	s_ashr_i32 s21, s20, 31
	v_and_b32_e32 v0, -16, v0
	v_lshlrev_b32_e32 v1, 5, v1
	v_sub_u32_e32 v2, v2, v3
	s_lshl_b32 s19, s16, 8
	s_lshl_b64 s[22:23], s[20:21], 12
	v_readlane_b32 s40, v248, 10
	v_add_u32_e32 v0, v4, v0
	v_and_b32_e32 v1, 32, v1
	v_ashrrev_i16_sdwa v2, v159, sext(v2) dst_sel:DWORD dst_unused:UNUSED_PAD src0_sel:DWORD src1_sel:BYTE_0
	v_readlane_b32 s41, v248, 11
	s_add_u32 s16, s40, s22
	v_add_u32_sdwa v2, v1, sext(v2) dst_sel:DWORD dst_unused:UNUSED_PAD src0_sel:DWORD src1_sel:WORD_0
	v_ashrrev_i32_e32 v1, 31, v0
	s_addc_u32 s17, s41, s23
	v_lshlrev_b64 v[0:1], 12, v[0:1]
	v_ashrrev_i32_e32 v3, 31, v2
	v_lshl_add_u64 v[4:5], s[16:17], 0, v[0:1]
	v_lshlrev_b64 v[2:3], 1, v[2:3]
	v_add_u32_e32 v21, 0x2000, v20
	v_lshl_add_u64 v[8:9], v[4:5], 0, v[2:3]
	v_ashrrev_i32_e32 v4, 31, v21
	v_lshrrev_b32_e32 v4, 22, v4
	v_add_u32_e32 v4, v21, v4
	v_ashrrev_i32_e32 v5, 10, v4
	v_mul_i32_i24_e32 v4, 0x400, v5
	v_sub_u32_e32 v4, v21, v4
	v_lshrrev_b32_e32 v6, 4, v4
	v_bitop3_b32 v6, v6, v4, 32 bitop3:0x6c
	v_ashrrev_i32_e32 v7, 31, v6
	v_lshrrev_b32_e32 v7, 26, v7
	v_add_u32_e32 v7, v6, v7
	v_lshlrev_b32_e32 v4, 3, v5
	v_ashrrev_i32_e32 v10, 6, v7
	v_and_b32_e32 v7, 0xc0, v7
	v_and_b32_e32 v4, -16, v4
	v_lshlrev_b32_e32 v5, 5, v5
	v_sub_u32_e32 v6, v6, v7
	v_add_u32_e32 v4, v10, v4
	v_and_b32_e32 v5, 32, v5
	v_ashrrev_i16_sdwa v6, v159, sext(v6) dst_sel:DWORD dst_unused:UNUSED_PAD src0_sel:DWORD src1_sel:BYTE_0
	v_add_u32_e32 v140, s28, v20
	v_add_u32_sdwa v6, v5, sext(v6) dst_sel:DWORD dst_unused:UNUSED_PAD src0_sel:DWORD src1_sel:WORD_0
	v_ashrrev_i32_e32 v5, 31, v4
	v_readfirstlane_b32 s24, v140
	v_lshlrev_b64 v[4:5], 12, v[4:5]
	v_add_u32_e32 v12, s28, v21
	s_mov_b32 m0, s24
	v_lshl_add_u64 v[10:11], s[16:17], 0, v[4:5]
	v_readfirstlane_b32 s16, v12
	global_load_lds_dwordx4 v[8:9], off
	s_mov_b32 m0, s16
	s_lshl_b32 s16, s18, 5
	s_and_b32 s16, s16, 0xfffffc00
	s_add_i32 s18, s19, s16
	s_ashr_i32 s19, s18, 31
	s_lshl_b64 s[24:25], s[18:19], 12
	v_ashrrev_i32_e32 v7, 31, v6
	s_add_u32 s16, s92, s24
	v_lshlrev_b64 v[6:7], 1, v[6:7]
	s_addc_u32 s17, s93, s25
	v_add_u32_e32 v141, 0, v20
	v_lshl_add_u64 v[10:11], v[10:11], 0, v[6:7]
	v_lshl_add_u64 v[12:13], s[16:17], 0, v[0:1]
	v_readfirstlane_b32 s19, v141
	v_add_u32_e32 v142, 0x2000, v141
	global_load_lds_dwordx4 v[10:11], off
	v_lshl_add_u64 v[12:13], v[12:13], 0, v[2:3]
	s_mov_b32 m0, s19
	v_lshl_add_u64 v[14:15], s[16:17], 0, v[4:5]
	v_readfirstlane_b32 s16, v142
	global_load_lds_dwordx4 v[12:13], off
	s_mov_b32 m0, s16
	s_or_b32 s16, s20, 0x80
	s_ashr_i32 s17, s16, 31
	s_lshl_b64 s[16:17], s[16:17], 12
	s_add_u32 s16, s40, s16
	s_addc_u32 s17, s41, s17
	v_add_u32_e32 v144, s29, v20
	v_lshl_add_u64 v[14:15], v[14:15], 0, v[6:7]
	v_lshl_add_u64 v[16:17], s[16:17], 0, v[0:1]
	v_readfirstlane_b32 s19, v144
	v_add_u32_e32 v21, s29, v21
	global_load_lds_dwordx4 v[14:15], off
	v_lshl_add_u64 v[16:17], v[16:17], 0, v[2:3]
	s_mov_b32 m0, s19
	v_lshl_add_u64 v[18:19], s[16:17], 0, v[4:5]
	v_readfirstlane_b32 s16, v21
	global_load_lds_dwordx4 v[16:17], off
	s_mov_b32 m0, s16
	s_or_b32 s16, s18, 0x80
	s_ashr_i32 s17, s16, 31
	s_lshl_b64 s[26:27], s[16:17], 12
	s_add_u32 s26, s92, s26
	s_addc_u32 s27, s93, s27
	v_add_u32_e32 v146, 0x4000, v141
	v_lshl_add_u64 v[18:19], v[18:19], 0, v[6:7]
	v_lshl_add_u64 v[22:23], s[26:27], 0, v[0:1]
	v_readfirstlane_b32 s17, v146
	v_add_u32_e32 v147, 0x6000, v141
	global_load_lds_dwordx4 v[18:19], off
	v_lshl_add_u64 v[128:129], v[22:23], 0, v[2:3]
	s_mov_b32 m0, s17
	v_lshl_add_u64 v[22:23], s[26:27], 0, v[4:5]
	v_readfirstlane_b32 s17, v147
	global_load_lds_dwordx4 v[128:129], off
	v_lshl_add_u64 v[130:131], v[22:23], 0, v[6:7]
	s_mov_b32 m0, s17
	v_ashrrev_i32_e32 v21, 8, v152
	global_load_lds_dwordx4 v[130:131], off
	v_mov_b64_e32 v[24:25], 0
	v_mov_b64_e32 v[26:27], 0
	v_mov_b64_e32 v[28:29], 0
	v_mov_b64_e32 v[30:31], 0
	v_mov_b64_e32 v[32:33], 0
	v_mov_b64_e32 v[34:35], 0
	v_mov_b64_e32 v[36:37], 0
	v_mov_b64_e32 v[38:39], 0
	v_mov_b64_e32 v[40:41], 0
	v_mov_b64_e32 v[42:43], 0
	v_mov_b64_e32 v[44:45], 0
	v_mov_b64_e32 v[46:47], 0
	v_mov_b64_e32 v[48:49], 0
	v_mov_b64_e32 v[50:51], 0
	v_mov_b64_e32 v[52:53], 0
	v_mov_b64_e32 v[54:55], 0
	v_mov_b64_e32 v[56:57], 0
	v_mov_b64_e32 v[58:59], 0
	v_mov_b64_e32 v[60:61], 0
	v_mov_b64_e32 v[62:63], 0
	v_mov_b64_e32 v[64:65], 0
	v_mov_b64_e32 v[66:67], 0
	v_mov_b64_e32 v[68:69], 0
	v_mov_b64_e32 v[70:71], 0
	v_mov_b64_e32 v[72:73], 0
	v_mov_b64_e32 v[74:75], 0
	v_mov_b64_e32 v[76:77], 0
	v_mov_b64_e32 v[78:79], 0
	v_mov_b64_e32 v[80:81], 0
	v_mov_b64_e32 v[82:83], 0
	v_mov_b64_e32 v[84:85], 0
	v_mov_b64_e32 v[86:87], 0
	v_mov_b64_e32 v[88:89], 0
	v_mov_b64_e32 v[90:91], 0
	v_mov_b64_e32 v[92:93], 0
	v_mov_b64_e32 v[94:95], 0
	v_mov_b64_e32 v[96:97], 0
	v_mov_b64_e32 v[98:99], 0
	v_mov_b64_e32 v[100:101], 0
	v_mov_b64_e32 v[102:103], 0
	v_mov_b64_e32 v[104:105], 0
	v_mov_b64_e32 v[106:107], 0
	v_mov_b64_e32 v[108:109], 0
	v_mov_b64_e32 v[110:111], 0
	v_mov_b64_e32 v[112:113], 0
	v_mov_b64_e32 v[114:115], 0
	v_mov_b64_e32 v[116:117], 0
	v_mov_b64_e32 v[118:119], 0
	v_mov_b64_e32 v[120:121], 0
	v_mov_b64_e32 v[122:123], 0
	v_mov_b64_e32 v[124:125], 0
	v_mov_b64_e32 v[126:127], 0
	v_cmp_eq_u32_e32 vcc, 1, v21
	v_readlane_b32 s42, v248, 12
	v_readlane_b32 s43, v248, 13
	v_readlane_b32 s44, v248, 14
	v_readlane_b32 s45, v248, 15
	v_readlane_b32 s46, v248, 16
	v_readlane_b32 s47, v248, 17
	v_readlane_b32 s48, v248, 18
	v_readlane_b32 s49, v248, 19
	v_readlane_b32 s50, v248, 20
	v_readlane_b32 s51, v248, 21
	v_readlane_b32 s52, v248, 22
	v_readlane_b32 s53, v248, 23
	v_readlane_b32 s54, v248, 24
	v_readlane_b32 s55, v248, 25
	s_and_saveexec_b64 s[26:27], vcc
	s_cbranch_execz .LBB0_434
	s_barrier
; #define WAIT_V(n) asm volatile("s_waitcnt vmcnt(" #n ")" ::: "memory")
; #define BAR __builtin_amdgcn_s_barrier()
;     ...
;     WAIT_V(4); BAR;
;     STAGE(SB(1, 0), Bt, bcol, 1); STAGE(SA(1, 0), A, brow, 1); STAGE(SB(1, 1), Bt, bcol + HALF, 1);
;     WAIT_V(6); BAR;
.LBB0_434:
	s_or_b64 exec, exec, s[26:27]
	v_add_u32_e32 v148, s30, v20
	v_add_u32_e32 v149, 0x2000, v148
	v_readfirstlane_b32 s17, v148
	v_lshl_add_u64 v[8:9], v[8:9], 0, s[2:3]
	s_mov_b32 m0, s17
	v_readfirstlane_b32 s17, v149
	v_add_u32_e32 v150, 0x8000, v141
	s_waitcnt vmcnt(2)
	s_barrier
	global_load_lds_dwordx4 v[8:9], off
	v_lshl_add_u64 v[8:9], v[10:11], 0, s[2:3]
	s_mov_b32 m0, s17
	v_readfirstlane_b32 s17, v150
	v_add_u32_e32 v151, 0xa000, v141
	global_load_lds_dwordx4 v[8:9], off
	v_lshl_add_u64 v[8:9], v[12:13], 0, s[2:3]
	s_mov_b32 m0, s17
	v_readfirstlane_b32 s17, v151
	v_add_u32_e32 v164, s31, v20
	global_load_lds_dwordx4 v[8:9], off
	v_lshl_add_u64 v[8:9], v[14:15], 0, s[2:3]
	s_mov_b32 m0, s17
	v_readfirstlane_b32 s17, v164
	v_add_u32_e32 v165, 0x2000, v164
	global_load_lds_dwordx4 v[8:9], off
	v_lshl_add_u64 v[8:9], v[16:17], 0, s[2:3]
	s_mov_b32 m0, s17
	v_readfirstlane_b32 s17, v165
	global_load_lds_dwordx4 v[8:9], off
	v_lshl_add_u64 v[8:9], v[18:19], 0, s[2:3]
	s_mov_b32 m0, s17
	v_and_b32_e32 v22, 15, v152
	global_load_lds_dwordx4 v[8:9], off
	v_lshlrev_b32_e32 v9, 2, v152
	v_and_b32_e32 v162, 48, v152
	v_lshlrev_b32_e32 v8, 6, v22
	v_and_b32_e32 v9, 32, v9
	v_bitop3_b32 v8, v8, v9, v162 bitop3:0x36
	v_add_u32_e32 v11, s28, v8
	v_add_u32_e32 v12, s29, v8
	v_add_u32_e32 v13, s30, v8
	v_add_u32_e32 v14, s31, v8
	v_add_u32_e32 v16, 0, v8
	v_lshlrev_b32_e32 v8, 6, v152
	v_and_or_b32 v8, v8, s33, v162
	v_xad_u32 v17, v8, v9, 0
	v_lshl_add_u64 v[8:9], s[22:23], 0, v[0:1]
	v_lshl_add_u64 v[0:1], s[24:25], 0, v[0:1]
	v_readlane_b32 s40, v248, 10
	v_lshl_add_u64 v[0:1], v[0:1], 0, v[2:3]
	v_ashrrev_i32_e32 v160, 6, v152
	v_lshl_add_u64 v[8:9], v[8:9], 0, v[2:3]
	v_readlane_b32 s41, v248, 11
	v_lshl_add_u64 v[136:137], s[92:93], 0, v[0:1]
	v_lshl_add_u64 v[0:1], s[24:25], 0, v[4:5]
	v_and_b32_e32 v161, 3, v160
	s_waitcnt vmcnt(6)
	v_lshlrev_b32_e32 v15, 13, v21
	v_lshl_add_u64 v[132:133], s[40:41], 0, v[8:9]
	v_lshl_add_u64 v[8:9], s[22:23], 0, v[4:5]
	v_lshl_add_u64 v[0:1], v[0:1], 0, v[6:7]
	v_lshlrev_b32_e32 v10, 12, v161
	v_or_b32_e32 v18, 0x800, v15
	v_or_b32_e32 v19, 0x1000, v15
	v_or_b32_e32 v20, 0x1800, v15
	v_lshl_add_u64 v[8:9], v[8:9], 0, v[6:7]
	v_lshl_add_u64 v[138:139], s[92:93], 0, v[0:1]
	v_mov_b32_e32 v0, 0
	v_lshl_or_b32 v163, v21, 6, v22
	v_lshl_add_u64 v[134:135], s[40:41], 0, v[8:9]
	s_mov_b32 s17, -2
	s_mov_b64 s[22:23], 0
	v_add_u32_e32 v167, v11, v10
	v_add_u32_e32 v157, v16, v15
	v_add_u32_e32 v156, v17, v18
	v_add_u32_e32 v155, v17, v19
	v_add_u32_e32 v154, v17, v20
	v_add_u32_e32 v166, v12, v10
	v_add_u32_e32 v145, v13, v10
	v_add_u32_e32 v143, v14, v10
	v_mov_b32_e32 v1, v0
	v_mov_b32_e32 v2, v0
	v_mov_b32_e32 v3, v0
	v_mov_b32_e32 v4, v0
	v_mov_b32_e32 v5, v0
	v_mov_b32_e32 v6, v0
	v_mov_b32_e32 v7, v0
	v_mov_b32_e32 v8, v0
	v_mov_b32_e32 v9, v0
	v_mov_b32_e32 v10, v0
	v_mov_b32_e32 v11, v0
	v_mov_b32_e32 v12, v0
	v_mov_b32_e32 v13, v0
	v_mov_b32_e32 v14, v0
	v_mov_b32_e32 v15, v0
	v_mov_b32_e32 v16, v0
	v_mov_b32_e32 v17, v0
	v_mov_b32_e32 v18, v0
	v_mov_b32_e32 v19, v0
	v_mov_b32_e32 v20, v0
	v_mov_b32_e32 v21, v0
	v_mov_b32_e32 v22, v0
	v_mov_b32_e32 v23, v0
	s_barrier
	v_readlane_b32 s42, v248, 12
	v_readlane_b32 s43, v248, 13
	v_readlane_b32 s44, v248, 14
	v_readlane_b32 s45, v248, 15
	v_readlane_b32 s46, v248, 16
	v_readlane_b32 s47, v248, 17
	v_readlane_b32 s48, v248, 18
	v_readlane_b32 s49, v248, 19
	v_readlane_b32 s50, v248, 20
	v_readlane_b32 s51, v248, 21
	v_readlane_b32 s52, v248, 22
	v_readlane_b32 s53, v248, 23
	v_readlane_b32 s54, v248, 24
	v_readlane_b32 s55, v248, 25

; #define BAR __builtin_amdgcn_s_barrier()
;     ...
;   for (int vw = blockIdx.x; vw < nwg; vw += gridDim.x) {
;     int tid_ = threadIdx.x;
;     asm volatile("" : "+v"(tid_));
;     const int wid = tid_ >> 6, lane = tid_ & 63, wr = wid >> 2, wc = wid & 3, fr = lane & 15, fq = lane >> 4;
;     int brow, bcol;
;     TILE_COORDS(vw, brow, bcol);
;     f32x4 acc[2][2][4][2] = {};
;     bf16x8 At[4][2], B0[2][2], B1[2][2];
;     STAGE(SB(0, 0), Bt, bcol, 0); STAGE(SA(0, 0), A, brow, 0);
;     STAGE(SB(0, 1), Bt, bcol + HALF, 0); STAGE(SA(0, 1), A, brow + HALF, 0);
;     if (wr == 1) BAR;
.LBB0_547:
	s_add_i32 s4, s23, s4
	v_ashrrev_i32_e32 v0, 31, v144
	s_ashr_i32 s5, s4, 31
	v_lshrrev_b32_e32 v0, 26, v0
	s_lshr_b32 s5, s5, 25
	v_add_u32_e32 v0, v144, v0
	s_add_i32 s26, s4, s5
	v_ashrrev_i32_e32 v1, 6, v0
	v_bfe_i32 v0, v144, 27, 1
	s_and_b32 s5, s26, 0xff80
	v_lshlrev_b32_e32 v151, 4, v144
	v_lshrrev_b32_e32 v0, 22, v0
	s_sub_i32 s4, s4, s5
	v_add_u32_e32 v0, v151, v0
	s_bfe_i32 s5, s4, 0x80000
	v_and_b32_e32 v0, 0xfffffc00, v0
	s_bfe_u32 s5, s5, 0x2000d
	v_sub_u32_e32 v0, v151, v0
	s_add_i32 s5, s4, s5
	v_lshrrev_b32_e32 v2, 4, v0
	s_bfe_i32 s22, s5, 0x80000
	s_and_b32 s5, s5, 0xfc
	v_bitop3_b32 v2, v2, v0, 32 bitop3:0x6c
	s_sub_i32 s4, s4, s5
	v_ashrrev_i32_e32 v3, 31, v2
	s_sext_i32_i16 s22, s22
	s_sext_i32_i8 s4, s4
	v_lshrrev_b32_e32 v3, 26, v3
	s_lshl_b32 s27, s4, 8
	s_lshl_b32 s4, s22, 6
	v_add_u32_e32 v3, v2, v3
	s_and_b32 s22, s4, 0xffffff00
	v_readlane_b32 s40, v248, 10
	v_lshlrev_b32_e32 v0, 3, v1
	v_ashrrev_i32_e32 v4, 6, v3
	v_and_b32_e32 v3, 0xc0, v3
	s_ashr_i32 s23, s22, 31
	v_readlane_b32 s42, v248, 12
	v_readlane_b32 s43, v248, 13
	v_and_b32_e32 v0, -16, v0
	v_lshlrev_b32_e32 v1, 5, v1
	v_sub_u32_e32 v2, v2, v3
	s_lshl_b64 s[4:5], s[22:23], 12
	s_mov_b64 s[38:39], s[42:43]
	v_add_u32_e32 v0, v4, v0
	v_and_b32_e32 v1, 32, v1
	v_ashrrev_i16_sdwa v2, v150, sext(v2) dst_sel:DWORD dst_unused:UNUSED_PAD src0_sel:DWORD src1_sel:BYTE_0
	s_add_u32 s24, s38, s4
	v_add_u32_sdwa v2, v1, sext(v2) dst_sel:DWORD dst_unused:UNUSED_PAD src0_sel:DWORD src1_sel:WORD_0
	v_ashrrev_i32_e32 v1, 31, v0
	s_addc_u32 s25, s39, s5
	v_lshlrev_b64 v[0:1], 12, v[0:1]
	v_ashrrev_i32_e32 v3, 31, v2
	v_lshl_add_u64 v[4:5], s[24:25], 0, v[0:1]
	v_lshlrev_b64 v[2:3], 1, v[2:3]
	v_add_u32_e32 v20, 0x2000, v151
	v_lshl_add_u64 v[8:9], v[4:5], 0, v[2:3]
	v_ashrrev_i32_e32 v4, 31, v20
	v_lshrrev_b32_e32 v4, 22, v4
	v_add_u32_e32 v4, v20, v4
	v_ashrrev_i32_e32 v5, 10, v4
	v_mul_i32_i24_e32 v4, 0x400, v5
	v_sub_u32_e32 v4, v20, v4
	v_lshrrev_b32_e32 v6, 4, v4
	v_bitop3_b32 v6, v6, v4, 32 bitop3:0x6c
	v_ashrrev_i32_e32 v7, 31, v6
	v_lshrrev_b32_e32 v7, 26, v7
	v_add_u32_e32 v7, v6, v7
	v_lshlrev_b32_e32 v4, 3, v5
	v_ashrrev_i32_e32 v10, 6, v7
	v_and_b32_e32 v7, 0xc0, v7
	v_and_b32_e32 v4, -16, v4
	v_lshlrev_b32_e32 v5, 5, v5
	v_sub_u32_e32 v6, v6, v7
	v_add_u32_e32 v4, v10, v4
	v_and_b32_e32 v5, 32, v5
	v_ashrrev_i16_sdwa v6, v150, sext(v6) dst_sel:DWORD dst_unused:UNUSED_PAD src0_sel:DWORD src1_sel:BYTE_0
	v_add_u32_e32 v140, s19, v151
	v_add_u32_sdwa v6, v5, sext(v6) dst_sel:DWORD dst_unused:UNUSED_PAD src0_sel:DWORD src1_sel:WORD_0
	v_ashrrev_i32_e32 v5, 31, v4
	v_readfirstlane_b32 s28, v140
	v_lshlrev_b64 v[4:5], 12, v[4:5]
	v_add_u32_e32 v12, s19, v20
	s_mov_b32 m0, s28
	v_lshl_add_u64 v[10:11], s[24:25], 0, v[4:5]
	v_readfirstlane_b32 s24, v12
	global_load_lds_dwordx4 v[8:9], off
	s_mov_b32 m0, s24
	s_lshl_b32 s24, s26, 3
	s_and_b32 s24, s24, 0xfffffc00
	s_add_i32 s24, s27, s24
	s_ashr_i32 s25, s24, 31
	s_lshl_b64 s[26:27], s[24:25], 12
	s_add_u32 s28, s90, s26
	s_addc_u32 s29, s91, s27
	v_lshl_add_u64 v[12:13], s[28:29], 0, v[0:1]
	v_lshl_add_u64 v[14:15], s[28:29], 0, v[4:5]
	s_or_b32 s28, s22, 0x80
	s_ashr_i32 s29, s28, 31
	s_lshl_b64 s[28:29], s[28:29], 12
	s_add_u32 s28, s38, s28
	v_ashrrev_i32_e32 v7, 31, v6
	s_addc_u32 s29, s39, s29
	v_lshlrev_b64 v[6:7], 1, v[6:7]
	v_add_u32_e32 v147, 0, v151
	v_lshl_add_u64 v[16:17], s[28:29], 0, v[0:1]
	v_lshl_add_u64 v[18:19], s[28:29], 0, v[4:5]
	s_or_b32 s28, s24, 0x80
	v_lshl_add_u64 v[10:11], v[10:11], 0, v[6:7]
	v_readfirstlane_b32 s25, v147
	v_add_u32_e32 v153, 0x2000, v147
	s_ashr_i32 s29, s28, 31
	global_load_lds_dwordx4 v[10:11], off
	v_lshl_add_u64 v[12:13], v[12:13], 0, v[2:3]
	s_mov_b32 m0, s25
	v_readfirstlane_b32 s25, v153
	v_add_u32_e32 v155, s21, v151
	s_lshl_b64 s[28:29], s[28:29], 12
	global_load_lds_dwordx4 v[12:13], off
	v_lshl_add_u64 v[14:15], v[14:15], 0, v[6:7]
	s_mov_b32 m0, s25
	v_readfirstlane_b32 s25, v155
	v_add_u32_e32 v20, s21, v20
	s_add_u32 s28, s90, s28
	global_load_lds_dwordx4 v[14:15], off
	v_lshl_add_u64 v[16:17], v[16:17], 0, v[2:3]
	s_mov_b32 m0, s25
	v_readfirstlane_b32 s25, v20
	s_addc_u32 s29, s91, s29
	v_add_u32_e32 v157, 0x4000, v147
	global_load_lds_dwordx4 v[16:17], off
	v_lshl_add_u64 v[18:19], v[18:19], 0, v[6:7]
	s_mov_b32 m0, s25
	v_lshl_add_u64 v[20:21], s[28:29], 0, v[0:1]
	v_readfirstlane_b32 s25, v157
	v_add_u32_e32 v158, 0x6000, v147
	global_load_lds_dwordx4 v[18:19], off
	v_lshl_add_u64 v[128:129], v[20:21], 0, v[2:3]
	s_mov_b32 m0, s25
	v_lshl_add_u64 v[20:21], s[28:29], 0, v[4:5]
	v_readfirstlane_b32 s25, v158
	global_load_lds_dwordx4 v[128:129], off
	v_lshl_add_u64 v[130:131], v[20:21], 0, v[6:7]
	s_mov_b32 m0, s25
	v_ashrrev_i32_e32 v20, 8, v144
	global_load_lds_dwordx4 v[130:131], off
	v_mov_b64_e32 v[22:23], 0
	v_mov_b64_e32 v[24:25], 0
	v_mov_b64_e32 v[26:27], 0
	v_mov_b64_e32 v[28:29], 0
	v_mov_b64_e32 v[30:31], 0
	v_mov_b64_e32 v[32:33], 0
	v_mov_b64_e32 v[34:35], 0
	v_mov_b64_e32 v[36:37], 0
	v_mov_b64_e32 v[38:39], 0
	v_mov_b64_e32 v[40:41], 0
	v_mov_b64_e32 v[42:43], 0
	v_mov_b64_e32 v[44:45], 0
	v_mov_b64_e32 v[46:47], 0
	v_mov_b64_e32 v[48:49], 0
	v_mov_b64_e32 v[50:51], 0
	v_mov_b64_e32 v[52:53], 0
	v_mov_b64_e32 v[54:55], 0
	v_mov_b64_e32 v[56:57], 0
	v_mov_b64_e32 v[58:59], 0
	v_mov_b64_e32 v[60:61], 0
	v_mov_b64_e32 v[62:63], 0
	v_mov_b64_e32 v[64:65], 0
	v_mov_b64_e32 v[66:67], 0
	v_mov_b64_e32 v[68:69], 0
	v_mov_b64_e32 v[70:71], 0
	v_mov_b64_e32 v[72:73], 0
	v_mov_b64_e32 v[74:75], 0
	v_mov_b64_e32 v[76:77], 0
	v_mov_b64_e32 v[78:79], 0
	v_mov_b64_e32 v[80:81], 0
	v_mov_b64_e32 v[82:83], 0
	v_mov_b64_e32 v[84:85], 0
	v_mov_b64_e32 v[86:87], 0
	v_mov_b64_e32 v[88:89], 0
	v_mov_b64_e32 v[90:91], 0
	v_mov_b64_e32 v[92:93], 0
	v_mov_b64_e32 v[94:95], 0
	v_mov_b64_e32 v[96:97], 0
	v_mov_b64_e32 v[98:99], 0
	v_mov_b64_e32 v[100:101], 0
	v_mov_b64_e32 v[102:103], 0
	v_mov_b64_e32 v[104:105], 0
	v_mov_b64_e32 v[106:107], 0
	v_mov_b64_e32 v[108:109], 0
	v_mov_b64_e32 v[110:111], 0
	v_mov_b64_e32 v[112:113], 0
	v_mov_b64_e32 v[114:115], 0
	v_mov_b64_e32 v[116:117], 0
	v_mov_b64_e32 v[118:119], 0
	v_mov_b64_e32 v[120:121], 0
	v_mov_b64_e32 v[122:123], 0
	v_mov_b64_e32 v[124:125], 0
	v_mov_b64_e32 v[126:127], 0
	v_cmp_eq_u32_e32 vcc, 1, v20
	v_readlane_b32 s41, v248, 11
	v_readlane_b32 s44, v248, 14
	v_readlane_b32 s45, v248, 15
	v_readlane_b32 s46, v248, 16
	v_readlane_b32 s47, v248, 17
	v_readlane_b32 s48, v248, 18
	v_readlane_b32 s49, v248, 19
	v_readlane_b32 s50, v248, 20
	v_readlane_b32 s51, v248, 21
	v_readlane_b32 s52, v248, 22
	v_readlane_b32 s53, v248, 23
	v_readlane_b32 s54, v248, 24
	v_readlane_b32 s55, v248, 25
	s_and_saveexec_b64 s[28:29], vcc
	s_cbranch_execz .LBB0_549
	s_barrier
; #define WAIT_V(n) asm volatile("s_waitcnt vmcnt(" #n ")" ::: "memory")
; #define BAR __builtin_amdgcn_s_barrier()
;     ...
;     WAIT_V(4); BAR;
;     STAGE(SB(1, 0), Bt, bcol, 1); STAGE(SA(1, 0), A, brow, 1); STAGE(SB(1, 1), Bt, bcol + HALF, 1);
;     WAIT_V(6); BAR;
.LBB0_549:
	s_or_b64 exec, exec, s[28:29]
	v_add_u32_e32 v159, s30, v151
	v_add_u32_e32 v160, 0x2000, v159
	v_readfirstlane_b32 s25, v159
	v_lshl_add_u64 v[8:9], v[8:9], 0, s[2:3]
	s_mov_b32 m0, s25
	v_readfirstlane_b32 s25, v160
	v_add_u32_e32 v161, 0x8000, v147
	s_waitcnt vmcnt(2)
	s_barrier
	global_load_lds_dwordx4 v[8:9], off
	v_lshl_add_u64 v[8:9], v[10:11], 0, s[2:3]
	s_mov_b32 m0, s25
	v_readfirstlane_b32 s25, v161
	v_add_u32_e32 v162, 0xa000, v147
	global_load_lds_dwordx4 v[8:9], off
	v_lshl_add_u64 v[8:9], v[12:13], 0, s[2:3]
	s_mov_b32 m0, s25
	v_readfirstlane_b32 s25, v162
	v_add_u32_e32 v163, s31, v151
	global_load_lds_dwordx4 v[8:9], off
	v_lshl_add_u64 v[8:9], v[14:15], 0, s[2:3]
	s_mov_b32 m0, s25
	v_readfirstlane_b32 s25, v163
	v_add_u32_e32 v164, 0x2000, v163
	global_load_lds_dwordx4 v[8:9], off
	v_lshl_add_u64 v[8:9], v[16:17], 0, s[2:3]
	s_mov_b32 m0, s25
	v_readfirstlane_b32 s25, v164
	global_load_lds_dwordx4 v[8:9], off
	v_lshl_add_u64 v[8:9], v[18:19], 0, s[2:3]
	s_mov_b32 m0, s25
	v_and_b32_e32 v21, 15, v144
	global_load_lds_dwordx4 v[8:9], off
	v_bfe_u32 v149, v144, 4, 2
	v_lshlrev_b32_e32 v11, 2, v144
	v_lshlrev_b32_e32 v8, 4, v149
	v_lshlrev_b32_e32 v9, 6, v21
	v_and_b32_e32 v11, 32, v11
	v_bitop3_b32 v9, v8, v11, v9 bitop3:0x36
	v_add_u32_e32 v12, s19, v9
	v_add_u32_e32 v13, s21, v9
	v_add_u32_e32 v14, s30, v9
	v_add_u32_e32 v15, s31, v9
	v_add_u32_e32 v17, 0, v9
	v_lshlrev_b32_e32 v9, 6, v144
	v_and_or_b32 v8, v9, s33, v8
	v_xad_u32 v11, v8, v11, 0
	v_lshl_add_u64 v[8:9], s[4:5], 0, v[0:1]
	v_readlane_b32 s40, v248, 10
	v_lshl_add_u64 v[0:1], s[26:27], 0, v[0:1]
	v_readlane_b32 s42, v248, 12
	v_readlane_b32 s43, v248, 13
	v_lshl_add_u64 v[0:1], v[0:1], 0, v[2:3]
	v_lshl_add_u64 v[8:9], v[8:9], 0, v[2:3]
	s_mov_b64 s[38:39], s[42:43]
	v_lshl_add_u64 v[136:137], s[90:91], 0, v[0:1]
	v_lshl_add_u64 v[0:1], s[26:27], 0, v[4:5]
	v_bfe_u32 v148, v144, 6, 2
	s_waitcnt vmcnt(6)
	v_lshlrev_b32_e32 v16, 13, v20
	v_lshl_add_u64 v[132:133], s[38:39], 0, v[8:9]
	v_lshl_add_u64 v[8:9], s[4:5], 0, v[4:5]
	v_lshl_add_u64 v[0:1], v[0:1], 0, v[6:7]
	v_lshlrev_b32_e32 v10, 12, v148
	v_lshl_or_b32 v152, v20, 6, v21
	v_or_b32_e32 v18, 0x800, v16
	v_or_b32_e32 v19, 0x1000, v16
	v_or_b32_e32 v20, 0x1800, v16
	v_lshl_add_u64 v[8:9], v[8:9], 0, v[6:7]
	v_lshl_add_u64 v[138:139], s[90:91], 0, v[0:1]
	v_mov_b32_e32 v0, 0
	v_lshl_add_u64 v[134:135], s[38:39], 0, v[8:9]
	s_mov_b32 s25, -2
	s_mov_b64 s[4:5], 0
	v_add_u32_e32 v166, v12, v10
	v_add_u32_e32 v146, v17, v16
	v_add_u32_e32 v143, v11, v18
	v_add_u32_e32 v142, v11, v19
	v_add_u32_e32 v141, v11, v20
	v_add_u32_e32 v165, v13, v10
	v_add_u32_e32 v156, v14, v10
	v_add_u32_e32 v154, v15, v10
	v_mov_b32_e32 v1, v0
	v_mov_b32_e32 v2, v0
	v_mov_b32_e32 v3, v0
	v_mov_b32_e32 v4, v0
	v_mov_b32_e32 v5, v0
	v_mov_b32_e32 v6, v0
	v_mov_b32_e32 v7, v0
	v_mov_b32_e32 v8, v0
	v_mov_b32_e32 v9, v0
	v_mov_b32_e32 v10, v0
	v_mov_b32_e32 v11, v0
	v_mov_b32_e32 v12, v0
	v_mov_b32_e32 v13, v0
	v_mov_b32_e32 v14, v0
	v_mov_b32_e32 v15, v0
	v_mov_b32_e32 v16, v0
	v_mov_b32_e32 v17, v0
	v_mov_b32_e32 v18, v0
	v_mov_b32_e32 v19, v0
	v_mov_b32_e32 v20, v0
	v_mov_b32_e32 v21, v0
	s_barrier
	v_readlane_b32 s41, v248, 11
	v_readlane_b32 s44, v248, 14
	v_readlane_b32 s45, v248, 15
	v_readlane_b32 s46, v248, 16
	v_readlane_b32 s47, v248, 17
	v_readlane_b32 s48, v248, 18
	v_readlane_b32 s49, v248, 19
	v_readlane_b32 s50, v248, 20
	v_readlane_b32 s51, v248, 21
	v_readlane_b32 s52, v248, 22
	v_readlane_b32 s53, v248, 23
	v_readlane_b32 s54, v248, 24
	v_readlane_b32 s55, v248, 25

; __device__ __forceinline__ void hgrn_block(const Params& p, int bh, char* smem) {
;   const int tid = opaque_tid(), lane = tid & 63, wid = tid >> 6, fr = lane & 15, fq = lane >> 4;
;   const int b = bh >> 4, h = bh & 15;
;   u16* QA = (u16*)smem;
;   u16* KB = QA + 64 * 136;
;   u16* QIN = KB + 64 * 136;
;   u16* KSTT = QIN + 64 * 136;
;   u16* VT = KSTT + 128 * 72;
;   u16* AT = VT + 128 * 72;
;   u16* STT = AT + 64 * 72;
;   float* dec = (float*)(STT + 128 * 136);
;   float* gsum = dec + 128;
;   float* ssq = gsum + 8 * 128;
;   for (int i = tid; i < 128 * 136 / 2; i += 512) ((unsigned*)STT)[i] = 0u;
;   f32x4 st[8];
; #pragma unroll
;   for (int i = 0; i < 8; ++i) st[i] = f32x4{0.f, 0.f, 0.f, 0.f};
;   const int d0 = lane * 2;
;   float lb[2];
; #pragma unroll
;   for (int e = 0; e < 2; ++e) {
;     float l0 = p.hgrn_lb[h * 128 + d0 + e], l1 = p.hgrn_lb[2048 + h * 128 + d0 + e];
;     lb[e] = 1.f / (1.f + __expf(l0 - l1));
;   }
;   const int tt = wid & 3, vh = wid >> 2;
;   unsigned rq[8], rf[8], rv[8];
;   uint2 rg[4];
;   {
;     const long tokb = (long)b * SEQ;
; #pragma unroll
;     for (int r = 0; r < 8; ++r) {
;       const u16* zr = p.Z + (tokb + wid * 8 + r) * LDZ1 + h * 128 + d0;
;       rq[r] = *(const unsigned*)zr; rf[r] = *(const unsigned*)(zr + 2048); rv[r] = *(const unsigned*)(zr + 4096);
;     }
;   }
.LBB0_597:
	s_or_b64 exec, exec, s[4:5]
	v_and_b32_e32 v5, 63, v4
	s_lshl_b32 s4, s76, 7
	s_and_b32 s6, s4, 0x780
	v_lshlrev_b32_e32 v28, 3, v5
	v_lshl_or_b32 v50, s6, 2, v28
	v_lshl_add_u64 v[0:1], s[80:81], 0, v[50:51]
	v_add_co_u32_e32 v0, vcc, s56, v0
	global_load_dwordx2 v[6:7], v50, s[80:81]
	s_nop 0
	v_addc_co_u32_e32 v1, vcc, 0, v1, vcc
	global_load_dwordx2 v[8:9], v[0:1], off
	v_ashrrev_i32_e32 v29, 6, v4
	s_ashr_i32 s44, s76, 4
	s_lshl_b32 s4, s33, 1
	s_ashr_i32 s45, s44, 31
	v_lshlrev_b32_e32 v0, 3, v29
	s_and_b32 s46, s4, 0xf00
	s_lshl_b64 s[4:5], s[44:45], 11
	v_ashrrev_i32_e32 v1, 31, v0
	s_lshl_b32 s6, s6, 1
	v_lshl_add_u64 v[2:3], s[4:5], 0, v[0:1]
	s_add_u32 s4, s88, s6
	v_lshlrev_b32_e32 v50, 2, v5
	s_addc_u32 s5, s89, 0
	v_lshlrev_b64 v[2:3], 14, v[2:3]
	s_waitcnt vmcnt(12)
	v_lshl_add_u64 v[10:11], s[4:5], 0, v[50:51]
	v_lshl_add_u64 v[2:3], v[10:11], 0, v[2:3]
	v_add_co_u32_e32 v10, vcc, s56, v2
	s_movk_i32 s4, 0x5000
	s_nop 0
	v_addc_co_u32_e32 v11, vcc, 0, v3, vcc
	s_waitcnt vmcnt(11)
	v_add_co_u32_e32 v12, vcc, s4, v2
	s_movk_i32 s4, 0x6000
	s_nop 0
	v_addc_co_u32_e32 v13, vcc, 0, v3, vcc
	v_add_co_u32_e32 v14, vcc, s4, v2
	s_mov_b32 s4, 0x9000
	s_nop 0
	v_addc_co_u32_e32 v15, vcc, 0, v3, vcc
	s_waitcnt vmcnt(10)
	v_add_co_u32_e32 v16, vcc, s4, v2
	s_mov_b32 s4, 0xa000
	s_nop 0
	v_addc_co_u32_e32 v17, vcc, 0, v3, vcc
	v_add_co_u32_e32 v18, vcc, s4, v2
	v_and_b32_e32 v30, 15, v4
	s_nop 0
	v_addc_co_u32_e32 v19, vcc, 0, v3, vcc
	v_add_co_u32_e32 v20, vcc, s57, v2
	v_bfe_u32 v31, v4, 4, 2
	s_nop 0
	v_addc_co_u32_e32 v21, vcc, 0, v3, vcc
	global_load_dword v111, v[10:11], off offset:-4096
	global_load_dword v157, v[10:11], off
	global_load_dword v162, v[12:13], off offset:-4096
	global_load_dword v112, v[12:13], off
	global_load_dword v161, v[16:17], off offset:-4096
	global_load_dword v115, v[16:17], off
	global_load_dword v160, v[20:21], off offset:-4096
	global_load_dword v119, v[20:21], off
	v_add_co_u32_e32 v22, vcc, s58, v2
	s_lshl_b64 s[42:43], s[44:45], 23
	s_nop 0
	v_addc_co_u32_e32 v23, vcc, 0, v3, vcc
	v_add_co_u32_e32 v24, vcc, s59, v2
	s_lshl_b64 s[44:45], s[44:45], 25
	s_nop 0
	v_addc_co_u32_e32 v25, vcc, 0, v3, vcc
	v_lshlrev_b64 v[0:1], 14, v[0:1]
	v_lshl_add_u64 v[0:1], s[44:45], 0, v[0:1]
	v_or_b32_e32 v0, v0, v50
	v_lshl_add_u64 v[60:61], s[88:89], 0, v[0:1]
	v_add_u32_e32 v113, s67, v28
	v_add_u32_e32 v120, s73, v28
	v_mul_u32_u24_e32 v28, 0x110, v30
	v_lshl_add_u32 v114, v29, 9, v113
	s_mov_b32 s77, 32
	v_cmp_lt_i32_e64 s[10:11], 1, v29
	v_cmp_lt_i32_e64 s[12:13], 2, v29
	v_cmp_lt_i32_e64 s[14:15], 3, v29
	v_cmp_lt_i32_e64 s[16:17], 4, v29
	v_cmp_lt_i32_e64 s[18:19], 5, v29
	v_cmp_lt_i32_e64 s[20:21], 6, v29
	v_cmp_lt_i32_e64 s[22:23], 7, v29
	s_waitcnt vmcnt(8)
	v_sub_f32_e32 v6, v6, v8
	v_sub_f32_e32 v7, v7, v9
	v_mul_f32_e32 v6, 0x3fb8aa3b, v6
	v_mul_f32_e32 v7, 0x3fb8aa3b, v7
	v_exp_f32_e32 v6, v6
	v_exp_f32_e32 v7, v7
	s_waitcnt vmcnt(6)
	v_mov_b32_e32 v136, v157
	v_pk_add_f32 v[6:7], v[6:7], 1.0 op_sel_hi:[1,0]
	s_waitcnt vmcnt(5)
	v_mov_b32_e32 v137, v162
	v_div_scale_f32 v8, s[4:5], v7, v7, 1.0
	v_div_scale_f32 v10, s[4:5], v6, v6, 1.0
	v_rcp_f32_e32 v11, v8
	v_rcp_f32_e32 v12, v10
	v_div_scale_f32 v9, vcc, 1.0, v7, 1.0
	v_fma_f32 v16, -v8, v11, 1.0
	v_fma_f32 v17, -v10, v12, 1.0
	v_fmac_f32_e32 v11, v16, v11
	v_div_scale_f32 v13, s[4:5], 1.0, v6, 1.0
	v_fmac_f32_e32 v12, v17, v12
	v_mul_f32_e32 v16, v9, v11
	v_mul_f32_e32 v17, v13, v12
	v_fma_f32 v20, -v8, v16, v9
	v_fma_f32 v21, -v10, v17, v13
	v_fmac_f32_e32 v16, v20, v11
	v_fmac_f32_e32 v17, v21, v12
	v_fma_f32 v8, -v8, v16, v9
	v_fma_f32 v9, -v10, v17, v13
	v_div_fmas_f32 v8, v8, v11, v16
	s_mov_b64 vcc, s[4:5]
	v_div_fixup_f32 v7, v8, v7, 1.0
	v_div_fmas_f32 v8, v9, v12, v17
	v_div_fixup_f32 v6, v8, v6, 1.0
	v_add_co_u32_e32 v8, vcc, s60, v2
	v_cmp_gt_u32_e64 s[4:5], 64, v4
	s_nop 0
	v_addc_co_u32_e32 v9, vcc, 0, v3, vcc
	v_add_co_u32_e32 v10, vcc, s61, v2
	v_pk_add_f32 v[56:57], v[6:7], 1.0 op_sel_hi:[1,0] neg_lo:[1,0] neg_hi:[1,0]
	s_nop 0
	v_addc_co_u32_e32 v11, vcc, 0, v3, vcc
	v_add_co_u32_e32 v12, vcc, s62, v2
	s_waitcnt vmcnt(3)
	v_mov_b32_e32 v140, v161
	v_addc_co_u32_e32 v13, vcc, 0, v3, vcc
	v_add_co_u32_e32 v16, vcc, s63, v2
	s_waitcnt vmcnt(1)
; __device__ __forceinline__ void hgrn_block(const Params& p, int bh, char* smem) {
;     ...
;   for (int i = tid; i < 128 * 136 / 2; i += 512) ((unsigned*)STT)[i] = 0u;
;   f32x4 st[8];
; #pragma unroll
;   for (int i = 0; i < 8; ++i) st[i] = f32x4{0.f, 0.f, 0.f, 0.f};
;   const int d0 = lane * 2;
;   float lb[2];
; #pragma unroll
;   for (int e = 0; e < 2; ++e) {
;     float l0 = p.hgrn_lb[h * 128 + d0 + e], l1 = p.hgrn_lb[2048 + h * 128 + d0 + e];
;     lb[e] = 1.f / (1.f + __expf(l0 - l1));
;   }
;   const int tt = wid & 3, vh = wid >> 2;
;   unsigned rq[8], rf[8], rv[8];
;   uint2 rg[4];
;   {
;     const long tokb = (long)b * SEQ;
; #pragma unroll
;     for (int r = 0; r < 8; ++r) {
;       const u16* zr = p.Z + (tokb + wid * 8 + r) * LDZ1 + h * 128 + d0;
;       rq[r] = *(const unsigned*)zr; rf[r] = *(const unsigned*)(zr + 2048); rv[r] = *(const unsigned*)(zr + 4096);
;     }
;   }
;   __syncthreads();
;   for (int c = 0; c < 32; ++c) {
;     ...
;         float4 og = *(const float4*)(p.out_gain + v);
	v_mov_b32_e32 v142, v160
	v_addc_co_u32_e32 v17, vcc, 0, v3, vcc
	v_add_co_u32_e32 v20, vcc, s64, v2
	s_nop 1
	v_addc_co_u32_e32 v21, vcc, 0, v3, vcc
	v_add_co_u32_e32 v26, vcc, s65, v2
	s_nop 1
	v_addc_co_u32_e32 v27, vcc, 0, v3, vcc
	global_load_dword v164, v[24:25], off offset:-4096
	global_load_dword v125, v[24:25], off
	global_load_dword v163, v[10:11], off offset:-4096
	global_load_dword v133, v[10:11], off
	global_load_dword v166, v[16:17], off offset:-4096
	global_load_dword v135, v[16:17], off
	global_load_dword v167, v[26:27], off offset:-4096
	global_load_dword v138, v[26:27], off
	v_add_co_u32_e32 v10, vcc, s66, v2
	v_and_b32_e32 v25, 0xffffff00, v4
	s_nop 0
	v_addc_co_u32_e32 v11, vcc, 0, v3, vcc
	global_load_dword v165, v[2:3], off
	global_load_dword v159, v[14:15], off
	global_load_dword v158, v[18:19], off
	global_load_dword v156, v[22:23], off
	global_load_dword v155, v[8:9], off
	global_load_dword v154, v[12:13], off
	global_load_dword v153, v[20:21], off
	global_load_dword v152, v[10:11], off
	v_lshlrev_b32_e32 v9, 4, v29
	v_and_b32_e32 v3, 48, v9
	v_ashrrev_i32_e32 v11, 7, v4
	v_lshlrev_b32_e32 v8, 1, v29
	v_and_b32_e32 v18, 48, v4
	v_or_b32_e32 v12, v3, v30
	v_and_b32_e32 v14, 2, v8
	v_lshl_or_b32 v15, v11, 4, v30
	v_add_u32_e32 v8, 0, v18
	v_mad_u64_u32 v[52:53], s[6:7], v15, s71, v[8:9]
	v_mul_u32_u24_e32 v10, 0x90, v12
	v_cmp_lt_i32_e32 vcc, v107, v108
	v_add3_u32 v53, s70, v10, v18
	v_lshlrev_b32_e32 v3, 2, v3
	v_cndmask_b32_e32 v10, v106, v107, vcc
	v_cmp_lt_i32_e32 vcc, v110, v108
	v_lshlrev_b32_e32 v117, 2, v10
	v_ashrrev_i32_e32 v2, 2, v4
	v_cndmask_b32_e32 v10, v106, v110, vcc
	v_lshlrev_b32_e32 v118, 2, v10
	v_lshlrev_b32_e32 v10, 2, v30
	v_add3_u32 v22, s72, v3, v10
	v_and_b32_e32 v3, 0xffffffc0, v4
	v_mul_lo_u32 v4, v29, s74
	v_add3_u32 v121, 0, v50, v4
	v_mul_u32_u24_e32 v4, 0x90, v5
	v_lshlrev_b32_e32 v4, 1, v4
	v_add3_u32 v122, 0, v9, v4
	v_add3_u32 v123, s68, v9, v4
	v_lshlrev_b32_e32 v4, 4, v14
	v_cmp_gt_u32_e64 s[6:7], 16, v5
	v_add_u32_e32 v23, s73, v3
	v_or_b32_e32 v3, v9, v30
	v_or_b32_e32 v5, v4, v30
	v_lshlrev_b32_e32 v13, 2, v31
	v_mad_u64_u32 v[54:55], s[8:9], v3, s69, v[8:9]
	v_mul_u32_u24_e32 v9, 0x110, v5
	v_or_b32_e32 v5, 16, v4
	v_or_b32_e32 v6, v5, v30
	v_or_b32_e32 v4, v4, v13
	v_cmp_le_i32_e64 s[24:25], v14, v11
	v_cmp_lt_i32_e64 s[26:27], v14, v11
	v_mul_u32_u24_e32 v14, 0x110, v6
	v_or_b32_e32 v6, 2, v4
	v_and_b32_e32 v2, 0xffffffc0, v2
	v_cmp_gt_i32_e64 s[34:35], v6, v15
	v_or_b32_e32 v6, 3, v4
	v_mul_lo_u32 v16, v15, s69
	v_or_b32_e32 v10, v13, v2
	v_cmp_gt_i32_e64 s[28:29], v4, v15
	v_cmp_lt_i32_e64 s[30:31], v4, v15
	v_cmp_gt_i32_e64 s[36:37], v6, v15
	v_lshlrev_b32_e32 v4, 1, v4
	v_or_b32_e32 v6, v5, v13
	v_lshlrev_b32_e32 v17, 3, v31
	v_lshlrev_b32_e32 v3, 5, v29
	v_ashrrev_i32_e32 v11, 31, v10
	v_add3_u32 v124, s70, v16, v4
	v_cmp_gt_i32_e64 s[38:39], v6, v15
	v_cmp_lt_i32_e64 s[40:41], v6, v15
	v_or_b32_e32 v7, 2, v6
	v_lshl_or_b32 v4, v12, 12, s42
	v_mov_b32_e32 v5, s43
	v_or_b32_e32 v13, 3, v6
	v_lshlrev_b32_e32 v6, 14, v12
	v_add3_u32 v24, s55, v3, v17
	v_ashrrev_i32_e32 v3, 31, v2
	v_cmp_gt_i32_e64 s[42:43], v7, v15
	v_or3_b32 v6, s44, v6, v17
	v_mov_b32_e32 v7, s45
	v_lshl_add_u64 v[0:1], v[10:11], 1, v[4:5]
	v_or_b32_e32 v19, v2, v30
	v_lshl_add_u64 v[62:63], s[92:93], 0, v[0:1]
	v_lshl_add_u64 v[0:1], v[2:3], 1, v[6:7]
	v_add_u32_e32 v20, s68, v18
	v_add_u32_e32 v21, s55, v18
	v_mul_lo_u32 v26, v19, s69
	v_mul_lo_u32 v19, v19, s71
	v_mul_u32_u24_e32 v27, 0x90, v30
	v_lshl_add_u64 v[64:65], s[2:3], 0, v[0:1]
	v_mov_b32_e32 v0, 0
	v_mad_u32_u24 v116, v12, s71, v8
	v_lshl_add_u32 v55, v12, 2, s72
	v_cmp_lt_i32_e64 s[8:9], 0, v29
	v_cmp_gt_i32_e64 s[44:45], v13, v15
	v_lshl_add_u64 v[58:59], v[10:11], 2, s[82:83]
	global_load_dwordx4 v[196:199], v[58:59], off
	global_load_dwordx4 v[200:203], v[58:59], off offset:64
	global_load_dwordx4 v[204:207], v[58:59], off offset:128
	global_load_dwordx4 v[208:211], v[58:59], off offset:192
	v_add_u32_e32 v50, v8, v9
	v_add_u32_e32 v126, v8, v14
	v_add_u32_e32 v127, v20, v26
	v_add_u32_e32 v128, v21, v19
	v_add_u32_e32 v129, v22, v25
	v_add_u32_e32 v130, v23, v18
	v_add_u32_e32 v131, v20, v27
	v_add_u32_e32 v132, v24, v28
	v_mov_b32_e32 v1, v0
	v_mov_b32_e32 v2, v0
	v_mov_b32_e32 v3, v0
	v_mov_b32_e32 v4, v0
	v_mov_b32_e32 v5, v0
	v_mov_b32_e32 v6, v0
	v_mov_b32_e32 v7, v0
	v_mov_b32_e32 v8, v0
	v_mov_b32_e32 v9, v0
	v_mov_b32_e32 v10, v0
	v_mov_b32_e32 v11, v0
	v_mov_b32_e32 v12, v0
	v_mov_b32_e32 v13, v0
	v_mov_b32_e32 v14, v0
	v_mov_b32_e32 v15, v0
	v_mov_b32_e32 v16, v0
	v_mov_b32_e32 v17, v0
	v_mov_b32_e32 v18, v0
	v_mov_b32_e32 v19, v0
	v_mov_b32_e32 v20, v0
	v_mov_b32_e32 v21, v0
	v_mov_b32_e32 v22, v0
	v_mov_b32_e32 v23, v0
	v_mov_b32_e32 v24, v0
	v_mov_b32_e32 v25, v0
	v_mov_b32_e32 v26, v0
	v_mov_b32_e32 v27, v0
	v_mov_b32_e32 v28, v0
	v_mov_b32_e32 v29, v0
	v_mov_b32_e32 v30, v0
	v_mov_b32_e32 v31, v0
	s_waitcnt vmcnt(6)
	v_mov_b32_e32 v139, v159
	s_waitcnt vmcnt(5)
	v_mov_b32_e32 v141, v158
	s_waitcnt vmcnt(4)
	v_mov_b32_e32 v143, v156
	s_waitcnt vmcnt(3)
	v_mov_b32_e32 v145, v155
	s_waitcnt vmcnt(2)
	v_mov_b32_e32 v147, v154
	s_waitcnt vmcnt(1)
	v_mov_b32_e32 v149, v153
	s_waitcnt vmcnt(0)
	v_mov_b32_e32 v151, v152
	v_mov_b32_e32 v134, v165
	v_mov_b32_e32 v144, v164
	v_mov_b32_e32 v146, v163
	v_mov_b32_e32 v148, v166
	v_mov_b32_e32 v150, v167
	s_waitcnt lgkmcnt(0)
	s_barrier
	s_branch .LBB0_599
; #define MFMA16(a, b, c) __builtin_amdgcn_mfma_f32_16x16x32_bf16((a), (b), (c), 0, 0, 0)
; __device__ __forceinline__ void hgrn_block(const Params& p, int bh, char* smem) {
;     ...
;     {
;       float dc[4];
; #pragma unroll
;       for (int j = 0; j < 4; ++j) dc[j] = dec[wid * 16 + fq * 4 + j];
; #pragma unroll
;       for (int vt = 0; vt < 8; ++vt) {
;         st[vt][0] *= dc[0]; st[vt][1] *= dc[1]; st[vt][2] *= dc[2]; st[vt][3] *= dc[3];
;       }
; #pragma unroll
;       for (int kk = 0; kk < 2; ++kk) {
;         bf16x8 kf = *(const bf16x8*)(KSTT + (wid * 16 + fr) * 72 + kk * 32 + fq * 8);
; #pragma unroll
;         for (int vt = 0; vt < 8; ++vt) {
;           bf16x8 vf = *(const bf16x8*)(VT + (vt * 16 + fr) * 72 + kk * 32 + fq * 8);
;           st[vt] = MFMA16(kf, vf, st[vt]);
;         }
;       }
;     }
.LBB0_598:
	s_or_b64 exec, exec, s[52:53]
	ds_read_b128 v[74:77], v130
	s_add_i32 s77, s77, -1
	v_lshl_add_u64 v[60:61], v[60:61], 0, s[48:49]
	v_lshl_add_u64 v[64:65], v[64:65], 0, s[48:49]
	s_cmp_lg_u32 s77, 0
	s_waitcnt lgkmcnt(0)
	v_pk_mul_f32 v[0:1], v[0:1], v[74:75]
	v_pk_mul_f32 v[2:3], v[2:3], v[76:77]
	v_pk_mul_f32 v[4:5], v[4:5], v[74:75]
	v_pk_mul_f32 v[6:7], v[6:7], v[76:77]
	v_pk_mul_f32 v[8:9], v[8:9], v[74:75]
	v_pk_mul_f32 v[10:11], v[10:11], v[76:77]
	v_pk_mul_f32 v[12:13], v[12:13], v[74:75]
	v_pk_mul_f32 v[14:15], v[14:15], v[76:77]
	v_pk_mul_f32 v[16:17], v[16:17], v[74:75]
	v_pk_mul_f32 v[18:19], v[18:19], v[76:77]
	v_pk_mul_f32 v[20:21], v[20:21], v[74:75]
	v_pk_mul_f32 v[22:23], v[22:23], v[76:77]
	v_pk_mul_f32 v[24:25], v[24:25], v[74:75]
	v_pk_mul_f32 v[26:27], v[26:27], v[76:77]
	v_pk_mul_f32 v[28:29], v[28:29], v[74:75]
	v_pk_mul_f32 v[30:31], v[30:31], v[76:77]
	ds_read_b128 v[74:77], v54 offset:52224
	ds_read_b128 v[78:81], v131
	s_waitcnt lgkmcnt(0)
	v_mfma_f32_16x16x32_bf16 v[0:3], v[74:77], v[78:81], v[0:3]
	ds_read_b128 v[78:81], v131 offset:2304
	s_waitcnt vmcnt(25)
	v_mov_b32_e32 v157, v136
	s_waitcnt vmcnt(22)
	v_mov_b32_e32 v159, v139
	s_waitcnt lgkmcnt(0)
	v_mfma_f32_16x16x32_bf16 v[4:7], v[74:77], v[78:81], v[4:7]
	ds_read_b128 v[78:81], v131 offset:4608
	s_waitcnt vmcnt(19)
	v_mov_b32_e32 v158, v141
	s_waitcnt vmcnt(16)
	v_mov_b32_e32 v156, v143
	s_waitcnt lgkmcnt(0)
	v_mfma_f32_16x16x32_bf16 v[8:11], v[74:77], v[78:81], v[8:11]
	ds_read_b128 v[78:81], v131 offset:6912
	s_waitcnt vmcnt(13)
	v_mov_b32_e32 v155, v145
	s_waitcnt vmcnt(10)
	v_mov_b32_e32 v154, v147
	s_waitcnt lgkmcnt(0)
	v_mfma_f32_16x16x32_bf16 v[12:15], v[74:77], v[78:81], v[12:15]
	ds_read_b128 v[78:81], v131 offset:9216
	s_waitcnt vmcnt(7)
	v_mov_b32_e32 v153, v149
	s_waitcnt vmcnt(4)
	v_mov_b32_e32 v152, v151
	s_waitcnt lgkmcnt(0)
	v_mfma_f32_16x16x32_bf16 v[16:19], v[74:77], v[78:81], v[16:19]
	ds_read_b128 v[78:81], v131 offset:11520
	v_mov_b32_e32 v165, v134
	v_mov_b32_e32 v162, v137
	s_waitcnt lgkmcnt(0)
	v_mfma_f32_16x16x32_bf16 v[20:23], v[74:77], v[78:81], v[20:23]
	ds_read_b128 v[78:81], v131 offset:13824
	v_mov_b32_e32 v161, v140
	v_mov_b32_e32 v160, v142
	s_waitcnt lgkmcnt(0)
	v_mfma_f32_16x16x32_bf16 v[24:27], v[74:77], v[78:81], v[24:27]
	ds_read_b128 v[78:81], v131 offset:16128
	v_mov_b32_e32 v164, v144
	v_mov_b32_e32 v163, v146
	s_waitcnt lgkmcnt(0)
	v_mfma_f32_16x16x32_bf16 v[28:31], v[74:77], v[78:81], v[28:31]
	ds_read_b128 v[74:77], v54 offset:52288
	ds_read_b128 v[78:81], v131 offset:64
	v_mov_b32_e32 v166, v148
	v_mov_b32_e32 v167, v150
	s_waitcnt lgkmcnt(0)
	v_mfma_f32_16x16x32_bf16 v[0:3], v[74:77], v[78:81], v[0:3]
	ds_read_b128 v[78:81], v131 offset:2368
	s_waitcnt lgkmcnt(0)
	v_mfma_f32_16x16x32_bf16 v[4:7], v[74:77], v[78:81], v[4:7]
	ds_read_b128 v[78:81], v131 offset:4672
	s_nop 3
	v_cvt_pk_bf16_f32 v48, v0, v1
	v_cvt_pk_bf16_f32 v49, v2, v3
	s_waitcnt lgkmcnt(0)
	v_mfma_f32_16x16x32_bf16 v[8:11], v[74:77], v[78:81], v[8:11]
	ds_read_b128 v[78:81], v131 offset:6976
	s_waitcnt lgkmcnt(0)
	v_mfma_f32_16x16x32_bf16 v[12:15], v[74:77], v[78:81], v[12:15]
	ds_read_b128 v[78:81], v131 offset:9280
	s_waitcnt lgkmcnt(0)
	v_mfma_f32_16x16x32_bf16 v[16:19], v[74:77], v[78:81], v[16:19]
	ds_read_b128 v[78:81], v131 offset:11584
	s_waitcnt lgkmcnt(0)
	v_mfma_f32_16x16x32_bf16 v[20:23], v[74:77], v[78:81], v[20:23]
	ds_read_b128 v[78:81], v131 offset:13888
	s_waitcnt lgkmcnt(0)
	v_mfma_f32_16x16x32_bf16 v[24:27], v[74:77], v[78:81], v[24:27]
	ds_read_b128 v[78:81], v131 offset:16192
	s_waitcnt lgkmcnt(0)
	s_barrier
; __device__ __forceinline__ float lo2f(unsigned u) { return __uint_as_float(u << 16); }
; __device__ __forceinline__ float hi2f(unsigned u) { return __uint_as_float(u & 0xffff0000u); }
; __device__ __forceinline__ float siluf_(float x) { return x * sigmoidf_(x); }
; __device__ __forceinline__ void hgrn_block(const Params& p, int bh, char* smem) {
;     ...
;     {
; #pragma unroll
;       for (int vt = 0; vt < 8; ++vt) {
;         uint2 o;
;         o.x = pack2(st[vt][0], st[vt][1]);
;         o.y = pack2(st[vt][2], st[vt][3]);
;         *(uint2*)(STT + (vt * 16 + fr) * 136 + wid * 16 + fq * 4) = o;
;       }
;     }
;     {
;       const int t = tt * 16 + fr;
;       float tot = ssq[t] + ssq[64 + t];
;       float rr = rsqrtf(tot * (1.f / 128.f) + EPS);
;       u16* op = p.MB + (tokb + t) * DM + h * 128;
; #pragma unroll
;       for (int i = 0; i < 4; ++i) {
;         const int v = (vh * 4 + i) * 16 + fq * 4;
;         float4 og = *(const float4*)(p.out_gain + v);
;         uint2 gg = rg[i];
;         uint2 w;
;         w.x = pack2(oc[i][0] * rr * og.x * siluf_(lo2f(gg.x)), oc[i][1] * rr * og.y * siluf_(hi2f(gg.x)));
;         w.y = pack2(oc[i][2] * rr * og.z * siluf_(lo2f(gg.y)), oc[i][3] * rr * og.w * siluf_(hi2f(gg.y)));
;         *(uint2*)(op + v) = w;
;       }
;     }
	v_mfma_f32_16x16x32_bf16 v[28:31], v[74:77], v[78:81], v[28:31]
	s_nop 1
	v_mov_b64_e32 v[76:77], v[196:197]
	v_mov_b64_e32 v[78:79], v[198:199]
	ds_write_b64 v132, v[48:49]
	v_cvt_pk_bf16_f32 v48, v4, v5
	v_cvt_pk_bf16_f32 v49, v6, v7
	ds_write_b64 v132, v[48:49] offset:4352
	v_cvt_pk_bf16_f32 v48, v8, v9
	v_cvt_pk_bf16_f32 v49, v10, v11
	ds_write_b64 v132, v[48:49] offset:8704
	v_cvt_pk_bf16_f32 v48, v12, v13
	v_cvt_pk_bf16_f32 v49, v14, v15
	ds_write_b64 v132, v[48:49] offset:13056
	v_cvt_pk_bf16_f32 v48, v16, v17
	v_cvt_pk_bf16_f32 v49, v18, v19
	ds_write_b64 v132, v[48:49] offset:17408
	v_cvt_pk_bf16_f32 v48, v20, v21
	v_cvt_pk_bf16_f32 v49, v22, v23
	ds_write_b64 v132, v[48:49] offset:21760
	v_cvt_pk_bf16_f32 v48, v24, v25
	v_cvt_pk_bf16_f32 v49, v26, v27
	ds_write_b64 v132, v[48:49] offset:26112
	v_cvt_pk_bf16_f32 v48, v28, v29
	v_cvt_pk_bf16_f32 v49, v30, v31
	ds_write_b64 v132, v[48:49] offset:30464
	ds_read2st64_b32 v[48:49], v55 offset1:1
	s_waitcnt vmcnt(3)
	v_lshlrev_b32_e32 v74, 16, v72
	v_and_b32_e32 v75, 0xffff0000, v72
	s_waitcnt lgkmcnt(0)
	v_add_f32_e32 v48, v48, v49
	v_fmamk_f32 v48, v48, 0x3c000000, v109
	v_cmp_gt_f32_e32 vcc, s75, v48
	v_mul_f32_e32 v49, 0x4b800000, v48
	s_nop 0
	v_cndmask_b32_e32 v48, v48, v49, vcc
	v_rsq_f32_e32 v48, v48
	s_nop 0
	v_mul_f32_e32 v49, 0x45800000, v48
	v_cndmask_b32_e32 v48, v48, v49, vcc
	v_mul_f32_e32 v49, 0xbfb8aa3b, v74
	v_exp_f32_e32 v49, v49
	s_nop 0
	v_add_f32_e32 v49, 1.0, v49
	v_rcp_f32_e32 v80, v49
	v_pk_mul_f32 v[44:45], v[44:45], v[48:49] op_sel_hi:[1,0]
	v_mul_f32_e32 v49, 0xbfb8aa3b, v75
	v_exp_f32_e32 v49, v49
	s_waitcnt vmcnt(0)
	v_pk_mul_f32 v[44:45], v[76:77], v[44:45]
	v_add_f32_e32 v49, 1.0, v49
	v_rcp_f32_e32 v81, v49
	s_nop 0
	v_pk_mul_f32 v[74:75], v[80:81], v[74:75]
	s_nop 0
	v_pk_mul_f32 v[44:45], v[74:75], v[44:45]
	s_nop 0
	v_cvt_pk_bf16_f32 v72, v44, v45
	v_lshlrev_b32_e32 v44, 16, v73
	v_mul_f32_e32 v49, 0xbfb8aa3b, v44
	v_exp_f32_e32 v49, v49
	v_and_b32_e32 v45, 0xffff0000, v73
	v_add_f32_e32 v49, 1.0, v49
	v_rcp_f32_e32 v74, v49
	v_pk_mul_f32 v[46:47], v[46:47], v[48:49] op_sel_hi:[1,0]
	v_mul_f32_e32 v49, 0xbfb8aa3b, v45
	v_exp_f32_e32 v49, v49
	v_pk_mul_f32 v[46:47], v[78:79], v[46:47]
	v_add_f32_e32 v49, 1.0, v49
	v_rcp_f32_e32 v75, v49
	s_nop 0
	v_pk_mul_f32 v[44:45], v[74:75], v[44:45]
	s_nop 0
	v_pk_mul_f32 v[44:45], v[44:45], v[46:47]
	v_lshlrev_b32_e32 v46, 16, v70
	v_cvt_pk_bf16_f32 v73, v44, v45
	v_lshl_add_u64 v[44:45], v[62:63], 0, s[46:47]
	global_store_dwordx2 v[44:45], v[72:73], off
	s_nop 1
	v_mov_b64_e32 v[72:73], v[200:201]
	v_mov_b64_e32 v[74:75], v[202:203]
	v_mul_f32_e32 v49, 0xbfb8aa3b, v46
	v_exp_f32_e32 v49, v49
	v_and_b32_e32 v47, 0xffff0000, v70
	v_lshl_add_u64 v[62:63], v[62:63], 0, s[50:51]
	v_add_f32_e32 v49, 1.0, v49
	v_rcp_f32_e32 v76, v49
	v_pk_mul_f32 v[40:41], v[40:41], v[48:49] op_sel_hi:[1,0]
	v_mul_f32_e32 v49, 0xbfb8aa3b, v47
	v_exp_f32_e32 v49, v49
	v_pk_mul_f32 v[40:41], v[72:73], v[40:41]
	v_add_f32_e32 v49, 1.0, v49
	v_rcp_f32_e32 v77, v49
	v_pk_mul_f32 v[42:43], v[42:43], v[48:49] op_sel_hi:[1,0]
	v_pk_mul_f32 v[46:47], v[76:77], v[46:47]
	s_nop 0
	v_pk_mul_f32 v[40:41], v[46:47], v[40:41]
	v_lshlrev_b32_e32 v46, 16, v71
	v_cvt_pk_bf16_f32 v40, v40, v41
	v_mul_f32_e32 v41, 0xbfb8aa3b, v46
	v_exp_f32_e32 v41, v41
	v_and_b32_e32 v47, 0xffff0000, v71
	v_pk_mul_f32 v[42:43], v[42:43], v[74:75]
	v_add_f32_e32 v41, 1.0, v41
	v_rcp_f32_e32 v70, v41
	v_mul_f32_e32 v41, 0xbfb8aa3b, v47
	v_exp_f32_e32 v41, v41
	s_nop 0
	v_add_f32_e32 v41, 1.0, v41
	v_rcp_f32_e32 v71, v41
	s_nop 0
	v_pk_mul_f32 v[46:47], v[70:71], v[46:47]
	s_nop 0
	v_pk_mul_f32 v[42:43], v[46:47], v[42:43]
	v_lshlrev_b32_e32 v46, 16, v68
	v_cvt_pk_bf16_f32 v41, v42, v43
	global_store_dwordx2 v[44:45], v[40:41], off offset:32
	s_nop 1
	v_mov_b64_e32 v[40:41], v[204:205]
	v_mov_b64_e32 v[42:43], v[206:207]
	v_mul_f32_e32 v49, 0xbfb8aa3b, v46
	v_exp_f32_e32 v49, v49
	v_and_b32_e32 v47, 0xffff0000, v68
	v_add_f32_e32 v49, 1.0, v49
	v_pk_mul_f32 v[36:37], v[36:37], v[48:49] op_sel_hi:[1,0]
	v_rcp_f32_e32 v70, v49
	v_pk_mul_f32 v[38:39], v[38:39], v[48:49] op_sel_hi:[1,0]
	v_pk_mul_f32 v[32:33], v[32:33], v[48:49] op_sel_hi:[1,0]
	v_pk_mul_f32 v[34:35], v[34:35], v[48:49] op_sel_hi:[1,0]
	v_pk_mul_f32 v[36:37], v[36:37], v[40:41]
	v_mul_f32_e32 v40, 0xbfb8aa3b, v47
	v_exp_f32_e32 v40, v40
	v_pk_mul_f32 v[38:39], v[38:39], v[42:43]
	v_add_f32_e32 v40, 1.0, v40
	v_rcp_f32_e32 v71, v40
	s_nop 0
	v_pk_mul_f32 v[40:41], v[70:71], v[46:47]
	s_nop 0
	v_pk_mul_f32 v[36:37], v[40:41], v[36:37]
	v_lshlrev_b32_e32 v40, 16, v69
	v_cvt_pk_bf16_f32 v36, v36, v37
	v_mul_f32_e32 v37, 0xbfb8aa3b, v40
	v_exp_f32_e32 v37, v37
	v_and_b32_e32 v41, 0xffff0000, v69
	v_add_f32_e32 v37, 1.0, v37
	v_rcp_f32_e32 v46, v37
	v_mul_f32_e32 v37, 0xbfb8aa3b, v41
	v_exp_f32_e32 v37, v37
	s_nop 0
	v_add_f32_e32 v37, 1.0, v37
	v_rcp_f32_e32 v47, v37
	s_nop 0
	v_pk_mul_f32 v[40:41], v[46:47], v[40:41]
	s_nop 0
	v_pk_mul_f32 v[38:39], v[40:41], v[38:39]
	v_lshlrev_b32_e32 v40, 16, v66
	v_cvt_pk_bf16_f32 v37, v38, v39
	global_store_dwordx2 v[44:45], v[36:37], off offset:64
	s_nop 1
	v_mov_b64_e32 v[36:37], v[208:209]
	v_mov_b64_e32 v[38:39], v[210:211]
	v_and_b32_e32 v41, 0xffff0000, v66
	v_mul_f32_e32 v42, 0xbfb8aa3b, v40
	v_exp_f32_e32 v42, v42
	v_pk_mul_f32 v[32:33], v[32:33], v[36:37]
	v_mul_f32_e32 v36, 0xbfb8aa3b, v41
	v_exp_f32_e32 v36, v36
	v_add_f32_e32 v42, 1.0, v42
	v_rcp_f32_e32 v42, v42
	v_pk_mul_f32 v[34:35], v[34:35], v[38:39]
	v_add_f32_e32 v36, 1.0, v36
	v_rcp_f32_e32 v43, v36
	s_nop 0
	v_pk_mul_f32 v[36:37], v[42:43], v[40:41]
	s_nop 0
	v_pk_mul_f32 v[32:33], v[36:37], v[32:33]
	v_lshlrev_b32_e32 v36, 16, v67
	v_cvt_pk_bf16_f32 v32, v32, v33
	v_mul_f32_e32 v33, 0xbfb8aa3b, v36
	v_exp_f32_e32 v33, v33
	v_and_b32_e32 v37, 0xffff0000, v67
	v_add_f32_e32 v33, 1.0, v33
	v_rcp_f32_e32 v40, v33
	v_mul_f32_e32 v33, 0xbfb8aa3b, v37
	v_exp_f32_e32 v33, v33
	s_nop 0
	v_add_f32_e32 v33, 1.0, v33
	v_rcp_f32_e32 v41, v33
	s_nop 0
	v_pk_mul_f32 v[36:37], v[40:41], v[36:37]
	s_nop 0
	v_pk_mul_f32 v[34:35], v[36:37], v[34:35]
	s_nop 0
	v_cvt_pk_bf16_f32 v33, v34, v35
	global_store_dwordx2 v[44:45], v[32:33], off offset:96
	s_cbranch_scc0 .LBB0_593

; #define BAR __builtin_amdgcn_s_barrier()
;     ...
;   for (int vw = blockIdx.x; vw < nwg; vw += gridDim.x) {
;     int tid_ = threadIdx.x;
;     asm volatile("" : "+v"(tid_));
;     const int wid = tid_ >> 6, lane = tid_ & 63, wr = wid >> 2, wc = wid & 3, fr = lane & 15, fq = lane >> 4;
;     int brow, bcol;
;     TILE_COORDS(vw, brow, bcol);
;     f32x4 acc[2][2][4][2] = {};
;     bf16x8 At[4][2], B0[2][2], B1[2][2];
;     STAGE(SB(0, 0), Bt, bcol, 0); STAGE(SA(0, 0), A, brow, 0);
;     STAGE(SB(0, 1), Bt, bcol + HALF, 0); STAGE(SA(0, 1), A, brow + HALF, 0);
;     if (wr == 1) BAR;
.LBB0_653:
	s_add_i32 s14, s17, s14
	v_ashrrev_i32_e32 v0, 31, v128
	s_ashr_i32 s15, s14, 31
	v_lshrrev_b32_e32 v0, 26, v0
	s_lshr_b32 s15, s15, 27
	v_add_u32_e32 v0, v128, v0
	s_add_i32 s16, s14, s15
	v_ashrrev_i32_e32 v1, 6, v0
	v_bfe_i32 v0, v128, 27, 1
	s_and_b32 s15, s16, 0xffe0
	v_lshlrev_b32_e32 v20, 4, v128
	v_lshrrev_b32_e32 v0, 22, v0
	s_sub_i32 s14, s14, s15
	v_add_u32_e32 v0, v20, v0
	s_bfe_i32 s15, s14, 0x80000
	v_and_b32_e32 v0, 0xfffffc00, v0
	s_bfe_u32 s15, s15, 0x2000d
	v_sub_u32_e32 v0, v20, v0
	s_add_i32 s15, s14, s15
	v_lshrrev_b32_e32 v2, 4, v0
	s_bfe_i32 s17, s15, 0x80000
	s_and_b32 s15, s15, 0xfc
	v_bitop3_b32 v2, v2, v0, 32 bitop3:0x6c
	s_sub_i32 s14, s14, s15
	v_ashrrev_i32_e32 v3, 31, v2
	s_sext_i32_i16 s17, s17
	s_sext_i32_i8 s14, s14
	v_lshrrev_b32_e32 v3, 26, v3
	s_lshl_b32 s22, s14, 8
	s_lshl_b32 s14, s17, 6
	v_add_u32_e32 v3, v2, v3
	s_and_b32 s18, s14, 0xffffff00
	v_readlane_b32 s40, v248, 10
	v_lshlrev_b32_e32 v0, 3, v1
	v_ashrrev_i32_e32 v4, 6, v3
	v_and_b32_e32 v3, 0xc0, v3
	s_ashr_i32 s19, s18, 31
	v_readlane_b32 s41, v248, 11
	v_readlane_b32 s44, v248, 14
	v_readlane_b32 s45, v248, 15
	v_and_b32_e32 v0, -16, v0
	v_lshlrev_b32_e32 v1, 5, v1
	v_sub_u32_e32 v2, v2, v3
	s_lshl_b64 s[20:21], s[18:19], 12
	s_mov_b64 s[40:41], s[44:45]
	v_add_u32_e32 v0, v4, v0
	v_and_b32_e32 v1, 32, v1
	v_ashrrev_i16_sdwa v2, v142, sext(v2) dst_sel:DWORD dst_unused:UNUSED_PAD src0_sel:DWORD src1_sel:BYTE_0
	s_add_u32 s14, s40, s20
	v_add_u32_sdwa v2, v1, sext(v2) dst_sel:DWORD dst_unused:UNUSED_PAD src0_sel:DWORD src1_sel:WORD_0
	v_ashrrev_i32_e32 v1, 31, v0
	s_addc_u32 s15, s41, s21
	v_lshlrev_b64 v[0:1], 12, v[0:1]
	v_ashrrev_i32_e32 v3, 31, v2
	v_lshl_add_u64 v[4:5], s[14:15], 0, v[0:1]
	v_lshlrev_b64 v[2:3], 1, v[2:3]
	v_add_u32_e32 v21, 0x2000, v20
	v_lshl_add_u64 v[8:9], v[4:5], 0, v[2:3]
	v_ashrrev_i32_e32 v4, 31, v21
	v_lshrrev_b32_e32 v4, 22, v4
	v_add_u32_e32 v4, v21, v4
	v_ashrrev_i32_e32 v5, 10, v4
	v_mul_i32_i24_e32 v4, 0x400, v5
	v_sub_u32_e32 v4, v21, v4
	v_lshrrev_b32_e32 v6, 4, v4
	v_bitop3_b32 v6, v6, v4, 32 bitop3:0x6c
	v_ashrrev_i32_e32 v7, 31, v6
	v_lshrrev_b32_e32 v7, 26, v7
	v_add_u32_e32 v7, v6, v7
	v_lshlrev_b32_e32 v4, 3, v5
	v_ashrrev_i32_e32 v10, 6, v7
	v_and_b32_e32 v7, 0xc0, v7
	v_and_b32_e32 v4, -16, v4
	v_lshlrev_b32_e32 v5, 5, v5
	v_sub_u32_e32 v6, v6, v7
	v_add_u32_e32 v4, v10, v4
	v_and_b32_e32 v5, 32, v5
	v_ashrrev_i16_sdwa v6, v142, sext(v6) dst_sel:DWORD dst_unused:UNUSED_PAD src0_sel:DWORD src1_sel:BYTE_0
	v_add_u32_e32 v147, s26, v20
	v_add_u32_sdwa v6, v5, sext(v6) dst_sel:DWORD dst_unused:UNUSED_PAD src0_sel:DWORD src1_sel:WORD_0
	v_ashrrev_i32_e32 v5, 31, v4
	v_readfirstlane_b32 s17, v147
	v_lshlrev_b64 v[4:5], 12, v[4:5]
	v_add_u32_e32 v12, s26, v21
	s_mov_b32 m0, s17
	v_lshl_add_u64 v[10:11], s[14:15], 0, v[4:5]
	v_readfirstlane_b32 s14, v12
	global_load_lds_dwordx4 v[8:9], off
	s_mov_b32 m0, s14
	s_lshl_b32 s14, s16, 5
	s_and_b32 s14, s14, 0xfffffc00
	s_add_i32 s16, s22, s14
	s_ashr_i32 s17, s16, 31
	s_lshl_b64 s[22:23], s[16:17], 12
	v_ashrrev_i32_e32 v7, 31, v6
	s_add_u32 s14, s92, s22
	v_lshlrev_b64 v[6:7], 1, v[6:7]
	s_addc_u32 s15, s93, s23
	v_add_u32_e32 v152, 0, v20
	v_lshl_add_u64 v[10:11], v[10:11], 0, v[6:7]
	v_lshl_add_u64 v[12:13], s[14:15], 0, v[0:1]
	v_readfirstlane_b32 s17, v152
	v_add_u32_e32 v153, 0x2000, v152
	global_load_lds_dwordx4 v[10:11], off
	v_lshl_add_u64 v[12:13], v[12:13], 0, v[2:3]
	s_mov_b32 m0, s17
	v_lshl_add_u64 v[14:15], s[14:15], 0, v[4:5]
	v_readfirstlane_b32 s14, v153
	global_load_lds_dwordx4 v[12:13], off
	s_mov_b32 m0, s14
	s_or_b32 s14, s18, 0x80
	s_ashr_i32 s15, s14, 31
	s_lshl_b64 s[14:15], s[14:15], 12
	s_add_u32 s14, s40, s14
	s_addc_u32 s15, s41, s15
	v_add_u32_e32 v155, s27, v20
	v_lshl_add_u64 v[14:15], v[14:15], 0, v[6:7]
	v_lshl_add_u64 v[16:17], s[14:15], 0, v[0:1]
	v_readfirstlane_b32 s17, v155
	v_add_u32_e32 v21, s27, v21
	global_load_lds_dwordx4 v[14:15], off
	v_lshl_add_u64 v[16:17], v[16:17], 0, v[2:3]
	s_mov_b32 m0, s17
	v_lshl_add_u64 v[18:19], s[14:15], 0, v[4:5]
	v_readfirstlane_b32 s14, v21
	global_load_lds_dwordx4 v[16:17], off
	s_mov_b32 m0, s14
	s_or_b32 s14, s16, 0x80
	s_ashr_i32 s15, s14, 31
	s_lshl_b64 s[24:25], s[14:15], 12
	s_add_u32 s24, s92, s24
	s_addc_u32 s25, s93, s25
	v_add_u32_e32 v157, 0x4000, v152
	v_lshl_add_u64 v[18:19], v[18:19], 0, v[6:7]
	v_lshl_add_u64 v[22:23], s[24:25], 0, v[0:1]
	v_readfirstlane_b32 s15, v157
	v_add_u32_e32 v158, 0x6000, v152
	global_load_lds_dwordx4 v[18:19], off
	v_lshl_add_u64 v[130:131], v[22:23], 0, v[2:3]
	s_mov_b32 m0, s15
	v_lshl_add_u64 v[22:23], s[24:25], 0, v[4:5]
	v_readfirstlane_b32 s15, v158
	global_load_lds_dwordx4 v[130:131], off
	v_lshl_add_u64 v[132:133], v[22:23], 0, v[6:7]
	s_mov_b32 m0, s15
	v_ashrrev_i32_e32 v21, 8, v128
	global_load_lds_dwordx4 v[132:133], off
	v_mov_b64_e32 v[24:25], 0
	v_mov_b64_e32 v[26:27], 0
	v_mov_b64_e32 v[28:29], 0
	v_mov_b64_e32 v[30:31], 0
	v_mov_b64_e32 v[32:33], 0
	v_mov_b64_e32 v[34:35], 0
	v_mov_b64_e32 v[36:37], 0
	v_mov_b64_e32 v[38:39], 0
	v_mov_b64_e32 v[40:41], 0
	v_mov_b64_e32 v[42:43], 0
	v_mov_b64_e32 v[44:45], 0
	v_mov_b64_e32 v[46:47], 0
	v_mov_b64_e32 v[48:49], 0
	v_mov_b64_e32 v[50:51], 0
	v_mov_b64_e32 v[52:53], 0
	v_mov_b64_e32 v[54:55], 0
	v_mov_b64_e32 v[56:57], 0
	v_mov_b64_e32 v[58:59], 0
	v_mov_b64_e32 v[60:61], 0
	v_mov_b64_e32 v[62:63], 0
	v_mov_b64_e32 v[64:65], 0
	v_mov_b64_e32 v[66:67], 0
	v_mov_b64_e32 v[68:69], 0
	v_mov_b64_e32 v[70:71], 0
	v_mov_b64_e32 v[72:73], 0
	v_mov_b64_e32 v[74:75], 0
	v_mov_b64_e32 v[76:77], 0
	v_mov_b64_e32 v[78:79], 0
	v_mov_b64_e32 v[80:81], 0
	v_mov_b64_e32 v[82:83], 0
	v_mov_b64_e32 v[84:85], 0
	v_mov_b64_e32 v[86:87], 0
	v_mov_b64_e32 v[88:89], 0
	v_mov_b64_e32 v[90:91], 0
	v_mov_b64_e32 v[92:93], 0
	v_mov_b64_e32 v[94:95], 0
	v_mov_b64_e32 v[96:97], 0
	v_mov_b64_e32 v[98:99], 0
	v_mov_b64_e32 v[100:101], 0
	v_mov_b64_e32 v[102:103], 0
	v_mov_b64_e32 v[104:105], 0
	v_mov_b64_e32 v[106:107], 0
	v_mov_b64_e32 v[108:109], 0
	v_mov_b64_e32 v[110:111], 0
	v_mov_b64_e32 v[112:113], 0
	v_mov_b64_e32 v[114:115], 0
	v_mov_b64_e32 v[116:117], 0
	v_mov_b64_e32 v[118:119], 0
	v_mov_b64_e32 v[120:121], 0
	v_mov_b64_e32 v[122:123], 0
	v_mov_b64_e32 v[124:125], 0
	v_mov_b64_e32 v[126:127], 0
	v_cmp_eq_u32_e32 vcc, 1, v21
	v_readlane_b32 s42, v248, 12
	v_readlane_b32 s43, v248, 13
	v_readlane_b32 s46, v248, 16
	v_readlane_b32 s47, v248, 17
	v_readlane_b32 s48, v248, 18
	v_readlane_b32 s49, v248, 19
	v_readlane_b32 s50, v248, 20
	v_readlane_b32 s51, v248, 21
	v_readlane_b32 s52, v248, 22
	v_readlane_b32 s53, v248, 23
	v_readlane_b32 s54, v248, 24
	v_readlane_b32 s55, v248, 25
	s_and_saveexec_b64 s[24:25], vcc
	s_cbranch_execz .LBB0_655
	s_barrier
; #define WAIT_V(n) asm volatile("s_waitcnt vmcnt(" #n ")" ::: "memory")
; #define BAR __builtin_amdgcn_s_barrier()
;     ...
;     WAIT_V(4); BAR;
;     STAGE(SB(1, 0), Bt, bcol, 1); STAGE(SA(1, 0), A, brow, 1); STAGE(SB(1, 1), Bt, bcol + HALF, 1);
;     WAIT_V(6); BAR;
.LBB0_655:
	s_or_b64 exec, exec, s[24:25]
	v_add_u32_e32 v159, s28, v20
	v_add_u32_e32 v160, 0x2000, v159
	v_readfirstlane_b32 s15, v159
	v_lshl_add_u64 v[8:9], v[8:9], 0, s[0:1]
	s_mov_b32 m0, s15
	v_readfirstlane_b32 s15, v160
	v_add_u32_e32 v161, 0x8000, v152
	s_waitcnt vmcnt(2)
	s_barrier
	global_load_lds_dwordx4 v[8:9], off
	v_lshl_add_u64 v[8:9], v[10:11], 0, s[0:1]
	s_mov_b32 m0, s15
	v_readfirstlane_b32 s15, v161
	v_add_u32_e32 v162, 0xa000, v152
	global_load_lds_dwordx4 v[8:9], off
	v_lshl_add_u64 v[8:9], v[12:13], 0, s[0:1]
	s_mov_b32 m0, s15
	v_readfirstlane_b32 s15, v162
	v_add_u32_e32 v163, s29, v20
	global_load_lds_dwordx4 v[8:9], off
	v_lshl_add_u64 v[8:9], v[14:15], 0, s[0:1]
	s_mov_b32 m0, s15
	v_readfirstlane_b32 s15, v163
	v_add_u32_e32 v164, 0x2000, v163
	global_load_lds_dwordx4 v[8:9], off
	v_lshl_add_u64 v[8:9], v[16:17], 0, s[0:1]
	s_mov_b32 m0, s15
	v_readfirstlane_b32 s15, v164
	global_load_lds_dwordx4 v[8:9], off
	v_lshl_add_u64 v[8:9], v[18:19], 0, s[0:1]
	s_mov_b32 m0, s15
	v_and_b32_e32 v22, 15, v128
	global_load_lds_dwordx4 v[8:9], off
	v_lshlrev_b32_e32 v9, 2, v128
	v_and_b32_e32 v145, 48, v128
	v_lshlrev_b32_e32 v8, 6, v22
	v_and_b32_e32 v9, 32, v9
	v_bitop3_b32 v8, v8, v9, v145 bitop3:0x36
	v_add_u32_e32 v11, s26, v8
	v_add_u32_e32 v12, s27, v8
	v_add_u32_e32 v13, s28, v8
	v_add_u32_e32 v14, s29, v8
	v_add_u32_e32 v16, 0, v8
	v_lshlrev_b32_e32 v8, 6, v128
	v_and_or_b32 v8, v8, s30, v145
	v_xad_u32 v17, v8, v9, 0
	v_lshl_add_u64 v[8:9], s[20:21], 0, v[0:1]
	v_readlane_b32 s40, v248, 10
	v_lshl_add_u64 v[0:1], s[22:23], 0, v[0:1]
	v_readlane_b32 s41, v248, 11
	v_readlane_b32 s44, v248, 14
	v_readlane_b32 s45, v248, 15
	v_lshl_add_u64 v[0:1], v[0:1], 0, v[2:3]
	v_ashrrev_i32_e32 v143, 6, v128
	v_lshl_add_u64 v[8:9], v[8:9], 0, v[2:3]
	s_mov_b64 s[40:41], s[44:45]
	v_lshl_add_u64 v[138:139], s[92:93], 0, v[0:1]
	v_lshl_add_u64 v[0:1], s[22:23], 0, v[4:5]
	v_and_b32_e32 v144, 3, v143
	s_waitcnt vmcnt(6)
	v_lshlrev_b32_e32 v15, 13, v21
	v_lshl_add_u64 v[134:135], s[40:41], 0, v[8:9]
	v_lshl_add_u64 v[8:9], s[20:21], 0, v[4:5]
	v_lshl_add_u64 v[0:1], v[0:1], 0, v[6:7]
	v_lshlrev_b32_e32 v10, 12, v144
	v_or_b32_e32 v18, 0x800, v15
	v_or_b32_e32 v19, 0x1000, v15
	v_or_b32_e32 v20, 0x1800, v15
	v_lshl_add_u64 v[8:9], v[8:9], 0, v[6:7]
	v_lshl_add_u64 v[140:141], s[92:93], 0, v[0:1]
	v_mov_b32_e32 v0, 0
	v_lshl_or_b32 v146, v21, 6, v22
	v_lshl_add_u64 v[136:137], s[40:41], 0, v[8:9]
	s_mov_b32 s15, -2
	s_mov_b64 s[20:21], 0
	v_add_u32_e32 v166, v11, v10
	v_add_u32_e32 v151, v16, v15
	v_add_u32_e32 v150, v17, v18
	v_add_u32_e32 v149, v17, v19
	v_add_u32_e32 v148, v17, v20
	v_add_u32_e32 v165, v12, v10
	v_add_u32_e32 v156, v13, v10
	v_add_u32_e32 v154, v14, v10
	v_mov_b32_e32 v1, v0
	v_mov_b32_e32 v2, v0
	v_mov_b32_e32 v3, v0
	v_mov_b32_e32 v4, v0
	v_mov_b32_e32 v5, v0
	v_mov_b32_e32 v6, v0
	v_mov_b32_e32 v7, v0
	v_mov_b32_e32 v8, v0
	v_mov_b32_e32 v9, v0
	v_mov_b32_e32 v10, v0
	v_mov_b32_e32 v11, v0
	v_mov_b32_e32 v12, v0
	v_mov_b32_e32 v13, v0
	v_mov_b32_e32 v14, v0
	v_mov_b32_e32 v15, v0
	v_mov_b32_e32 v16, v0
	v_mov_b32_e32 v17, v0
	v_mov_b32_e32 v18, v0
	v_mov_b32_e32 v19, v0
	v_mov_b32_e32 v20, v0
	v_mov_b32_e32 v21, v0
	v_mov_b32_e32 v22, v0
	v_mov_b32_e32 v23, v0
	s_barrier
	v_readlane_b32 s42, v248, 12
	v_readlane_b32 s43, v248, 13
	v_readlane_b32 s46, v248, 16
	v_readlane_b32 s47, v248, 17
	v_readlane_b32 s48, v248, 18
	v_readlane_b32 s49, v248, 19
	v_readlane_b32 s50, v248, 20
	v_readlane_b32 s51, v248, 21
	v_readlane_b32 s52, v248, 22
	v_readlane_b32 s53, v248, 23
	v_readlane_b32 s54, v248, 24
	v_readlane_b32 s55, v248, 25
